# wt3_pz_ss + in every GEMM epilogue the leading half issues the first load block before the unit-end barrier
# baseline (speedup 1.0000x reference)
.LBB0_864:
	s_add_u32 s4, s68, 0xfffc0080
	s_addc_u32 s5, s69, -1
	s_add_i32 s45, 0, 0x10000
	s_cmp_eq_u32 s97, 12
	s_cselect_b32 s75, s57, s5
	s_cselect_b32 s74, s95, s4
	s_cselect_b32 s71, s31, s96
	s_cselect_b32 s70, vcc_lo, vcc_hi
	s_add_i32 s6, 0, 0x14000
	v_add_u32_e32 v104, s45, v239
	v_add_u32_e32 v128, s6, v239
	ds_read_b128 v[90:93], v104
	ds_read_b128 v[94:97], v104 offset:1024
	ds_read_b128 v[100:103], v104 offset:2048
	ds_read_b128 v[104:107], v104 offset:3072
	ds_read_b128 v[108:111], v128
	ds_read_b128 v[112:115], v128 offset:1024
	ds_read_b128 v[120:123], v128 offset:2048
	ds_read_b128 v[128:131], v128 offset:3072
	s_add_i32 s44, s91, 0
	v_lshl_add_u64 v[200:201], s[68:69], 0, v[98:99]
	s_add_i32 m0, s44, 0xc000
	ds_read_b128 v[164:167], v241
	ds_read_b128 v[168:171], v241 offset:1024
	ds_read_b128 v[172:175], v241 offset:2048
	ds_read_b128 v[176:179], v241 offset:3072
	ds_read_b128 v[180:183], v241 offset:4096
	ds_read_b128 v[184:187], v241 offset:5120
	ds_read_b128 v[188:191], v241 offset:6144
	ds_read_b128 v[192:195], v241 offset:7168
	global_load_lds_dwordx4 v[200:201], off
	v_lshl_add_u64 v[200:201], s[68:69], 0, v[206:207]
	s_add_i32 m0, s44, 0xe000
	s_nop 0
	global_load_lds_dwordx4 v[200:201], off
	s_waitcnt vmcnt(8)
	s_waitcnt lgkmcnt(0)
	s_setprio 1
	s_barrier
	v_mfma_f32_16x16x32_bf16 v[160:163], v[90:93], v[164:167], v[160:163]
	v_mfma_f32_16x16x32_bf16 v[156:159], v[100:103], v[164:167], v[156:159]
	v_mfma_f32_16x16x32_bf16 v[144:147], v[90:93], v[172:175], v[144:147]
	v_mfma_f32_16x16x32_bf16 v[140:143], v[100:103], v[172:175], v[140:143]
	v_mfma_f32_16x16x32_bf16 v[124:127], v[90:93], v[180:183], v[124:127]
	v_mfma_f32_16x16x32_bf16 v[116:119], v[100:103], v[180:183], v[116:119]
	v_mfma_f32_16x16x32_bf16 v[78:81], v[90:93], v[188:191], v[78:81]
	v_mfma_f32_16x16x32_bf16 v[74:77], v[100:103], v[188:191], v[74:77]
	v_mfma_f32_16x16x32_bf16 v[160:163], v[94:97], v[168:171], v[160:163]
	v_mfma_f32_16x16x32_bf16 v[156:159], v[104:107], v[168:171], v[156:159]
	v_mfma_f32_16x16x32_bf16 v[144:147], v[94:97], v[176:179], v[144:147]
	v_mfma_f32_16x16x32_bf16 v[140:143], v[104:107], v[176:179], v[140:143]
	v_mfma_f32_16x16x32_bf16 v[124:127], v[94:97], v[184:187], v[124:127]
	v_mfma_f32_16x16x32_bf16 v[116:119], v[104:107], v[184:187], v[116:119]
	v_mfma_f32_16x16x32_bf16 v[78:81], v[94:97], v[192:195], v[78:81]
	v_mfma_f32_16x16x32_bf16 v[74:77], v[104:107], v[192:195], v[74:77]
	s_setprio 0
	s_setprio 1
	v_mfma_f32_16x16x32_bf16 v[152:155], v[108:111], v[164:167], v[152:155]
	v_mfma_f32_16x16x32_bf16 v[148:151], v[120:123], v[164:167], v[148:151]
	v_mfma_f32_16x16x32_bf16 v[136:139], v[108:111], v[172:175], v[136:139]
	v_mfma_f32_16x16x32_bf16 v[132:135], v[120:123], v[172:175], v[132:135]
	v_mfma_f32_16x16x32_bf16 v[86:89], v[108:111], v[180:183], v[86:89]
	v_mfma_f32_16x16x32_bf16 v[82:85], v[120:123], v[180:183], v[82:85]
	v_mfma_f32_16x16x32_bf16 v[70:73], v[108:111], v[188:191], v[70:73]
	v_mfma_f32_16x16x32_bf16 v[66:69], v[120:123], v[188:191], v[66:69]
	v_mfma_f32_16x16x32_bf16 v[152:155], v[112:115], v[168:171], v[152:155]
	v_mfma_f32_16x16x32_bf16 v[148:151], v[128:131], v[168:171], v[148:151]
	v_mfma_f32_16x16x32_bf16 v[136:139], v[112:115], v[176:179], v[136:139]
	v_mfma_f32_16x16x32_bf16 v[132:135], v[128:131], v[176:179], v[132:135]
	v_mfma_f32_16x16x32_bf16 v[86:89], v[112:115], v[184:187], v[86:89]
	v_mfma_f32_16x16x32_bf16 v[82:85], v[128:131], v[184:187], v[82:85]
	v_mfma_f32_16x16x32_bf16 v[70:73], v[112:115], v[192:195], v[70:73]
	v_mfma_f32_16x16x32_bf16 v[66:69], v[128:131], v[192:195], v[66:69]
	s_setprio 0
	s_barrier
	s_add_i32 s4, s45, s91
	v_lshl_add_u64 v[200:201], s[70:71], 0, v[204:205]
	s_mov_b32 m0, s4
	ds_read_b128 v[164:167], v241 offset:16384
	ds_read_b128 v[168:171], v241 offset:17408
	ds_read_b128 v[172:175], v241 offset:18432
	ds_read_b128 v[176:179], v241 offset:19456
	ds_read_b128 v[180:183], v241 offset:20480
	ds_read_b128 v[184:187], v241 offset:21504
	ds_read_b128 v[188:191], v241 offset:22528
	ds_read_b128 v[192:195], v241 offset:23552
	global_load_lds_dwordx4 v[200:201], off
	s_add_i32 m0, s4, 0x2000
	s_add_u32 s4, s70, 0x40000
	v_lshl_add_u64 v[202:203], s[70:71], 0, v[208:209]
	s_addc_u32 s5, s71, 0
	s_add_i32 s6, s6, s91
	global_load_lds_dwordx4 v[202:203], off
	v_lshl_add_u64 v[210:211], s[4:5], 0, v[204:205]
	s_mov_b32 m0, s6
	v_lshl_add_u64 v[212:213], s[74:75], 0, v[206:207]
	global_load_lds_dwordx4 v[210:211], off
	v_lshl_add_u64 v[210:211], s[4:5], 0, v[208:209]
	s_add_i32 m0, s6, 0x2000
	s_nop 0
	global_load_lds_dwordx4 v[210:211], off
	v_lshl_add_u64 v[210:211], s[74:75], 0, v[98:99]
	s_mov_b32 m0, s44
	s_nop 0
	global_load_lds_dwordx4 v[210:211], off
	s_add_i32 m0, s44, 0x2000
	s_nop 0
	global_load_lds_dwordx4 v[212:213], off
	s_waitcnt vmcnt(8)
	s_waitcnt lgkmcnt(0)
	s_setprio 1
	s_barrier
	v_mfma_f32_16x16x32_bf16 v[62:65], v[90:93], v[164:167], v[62:65]
	v_mfma_f32_16x16x32_bf16 v[58:61], v[100:103], v[164:167], v[58:61]
	v_mfma_f32_16x16x32_bf16 v[46:49], v[90:93], v[172:175], v[46:49]
	v_mfma_f32_16x16x32_bf16 v[42:45], v[100:103], v[172:175], v[42:45]
	v_mfma_f32_16x16x32_bf16 v[30:33], v[90:93], v[180:183], v[30:33]
	v_mfma_f32_16x16x32_bf16 v[26:29], v[100:103], v[180:183], v[26:29]
	v_mfma_f32_16x16x32_bf16 v[14:17], v[90:93], v[188:191], v[14:17]
	v_mfma_f32_16x16x32_bf16 v[10:13], v[100:103], v[188:191], v[10:13]
	v_mfma_f32_16x16x32_bf16 v[62:65], v[94:97], v[168:171], v[62:65]
	v_mfma_f32_16x16x32_bf16 v[58:61], v[104:107], v[168:171], v[58:61]
	v_mfma_f32_16x16x32_bf16 v[46:49], v[94:97], v[176:179], v[46:49]
	v_mfma_f32_16x16x32_bf16 v[42:45], v[104:107], v[176:179], v[42:45]
	v_mfma_f32_16x16x32_bf16 v[30:33], v[94:97], v[184:187], v[30:33]
	v_mfma_f32_16x16x32_bf16 v[26:29], v[104:107], v[184:187], v[26:29]
	v_mfma_f32_16x16x32_bf16 v[14:17], v[94:97], v[192:195], v[14:17]
	v_mfma_f32_16x16x32_bf16 v[10:13], v[104:107], v[192:195], v[10:13]
	s_setprio 0
	s_setprio 1
	v_mfma_f32_16x16x32_bf16 v[54:57], v[108:111], v[164:167], v[54:57]
	v_mfma_f32_16x16x32_bf16 v[50:53], v[120:123], v[164:167], v[50:53]
	v_mfma_f32_16x16x32_bf16 v[38:41], v[108:111], v[172:175], v[38:41]
	v_mfma_f32_16x16x32_bf16 v[34:37], v[120:123], v[172:175], v[34:37]
	v_mfma_f32_16x16x32_bf16 v[22:25], v[108:111], v[180:183], v[22:25]
	v_mfma_f32_16x16x32_bf16 v[18:21], v[120:123], v[180:183], v[18:21]
	v_mfma_f32_16x16x32_bf16 v[6:9], v[108:111], v[188:191], v[6:9]
	v_mfma_f32_16x16x32_bf16 v[2:5], v[120:123], v[188:191], v[2:5]
	v_mfma_f32_16x16x32_bf16 v[54:57], v[112:115], v[168:171], v[54:57]
	v_mfma_f32_16x16x32_bf16 v[50:53], v[128:131], v[168:171], v[50:53]
	v_mfma_f32_16x16x32_bf16 v[38:41], v[112:115], v[176:179], v[38:41]
	v_mfma_f32_16x16x32_bf16 v[34:37], v[128:131], v[176:179], v[34:37]
	v_mfma_f32_16x16x32_bf16 v[22:25], v[112:115], v[184:187], v[22:25]
	v_mfma_f32_16x16x32_bf16 v[18:21], v[128:131], v[184:187], v[18:21]
	v_mfma_f32_16x16x32_bf16 v[6:9], v[112:115], v[192:195], v[6:9]
	v_mfma_f32_16x16x32_bf16 v[2:5], v[128:131], v[192:195], v[2:5]
	s_setprio 0
	s_barrier
	s_add_i32 s6, 0, 0x18000
	s_add_i32 s7, 0, 0x1c000
	v_add_u32_e32 v104, s6, v239
	v_add_u32_e32 v128, s7, v239
	ds_read_b128 v[90:93], v104
	ds_read_b128 v[94:97], v104 offset:1024
	ds_read_b128 v[100:103], v104 offset:2048
	ds_read_b128 v[104:107], v104 offset:3072
	ds_read_b128 v[108:111], v128
	ds_read_b128 v[112:115], v128 offset:1024
	ds_read_b128 v[120:123], v128 offset:2048
	ds_read_b128 v[128:131], v128 offset:3072
	s_add_u32 s4, s74, 0x40000
	s_addc_u32 s5, s75, 0
	v_lshl_add_u64 v[214:215], s[4:5], 0, v[98:99]
	s_add_i32 m0, s44, 0x4000
	ds_read_b128 v[164:167], v241 offset:32768
	ds_read_b128 v[168:171], v241 offset:33792
	ds_read_b128 v[172:175], v241 offset:34816
	ds_read_b128 v[176:179], v241 offset:35840
	ds_read_b128 v[180:183], v241 offset:36864
	ds_read_b128 v[184:187], v241 offset:37888
	ds_read_b128 v[188:191], v241 offset:38912
	ds_read_b128 v[192:195], v241 offset:39936
	global_load_lds_dwordx4 v[214:215], off
	v_lshl_add_u64 v[214:215], s[4:5], 0, v[206:207]
	s_add_i32 m0, s44, 0x6000
	s_nop 0
	global_load_lds_dwordx4 v[214:215], off
	s_waitcnt vmcnt(8)
	s_waitcnt lgkmcnt(0)
	s_setprio 1
	s_barrier
	v_mfma_f32_16x16x32_bf16 v[160:163], v[90:93], v[164:167], v[160:163]
	v_mfma_f32_16x16x32_bf16 v[156:159], v[100:103], v[164:167], v[156:159]
	v_mfma_f32_16x16x32_bf16 v[144:147], v[90:93], v[172:175], v[144:147]
	v_mfma_f32_16x16x32_bf16 v[140:143], v[100:103], v[172:175], v[140:143]
	v_mfma_f32_16x16x32_bf16 v[124:127], v[90:93], v[180:183], v[124:127]
	v_mfma_f32_16x16x32_bf16 v[116:119], v[100:103], v[180:183], v[116:119]
	v_mfma_f32_16x16x32_bf16 v[78:81], v[90:93], v[188:191], v[78:81]
	v_mfma_f32_16x16x32_bf16 v[74:77], v[100:103], v[188:191], v[74:77]
	v_mfma_f32_16x16x32_bf16 v[160:163], v[94:97], v[168:171], v[160:163]
	v_mfma_f32_16x16x32_bf16 v[156:159], v[104:107], v[168:171], v[156:159]
	v_mfma_f32_16x16x32_bf16 v[144:147], v[94:97], v[176:179], v[144:147]
	v_mfma_f32_16x16x32_bf16 v[140:143], v[104:107], v[176:179], v[140:143]
	v_mfma_f32_16x16x32_bf16 v[124:127], v[94:97], v[184:187], v[124:127]
	v_mfma_f32_16x16x32_bf16 v[116:119], v[104:107], v[184:187], v[116:119]
	v_mfma_f32_16x16x32_bf16 v[78:81], v[94:97], v[192:195], v[78:81]
	v_mfma_f32_16x16x32_bf16 v[74:77], v[104:107], v[192:195], v[74:77]
	s_setprio 0
	s_setprio 1
	v_mfma_f32_16x16x32_bf16 v[152:155], v[108:111], v[164:167], v[152:155]
	v_mfma_f32_16x16x32_bf16 v[148:151], v[120:123], v[164:167], v[148:151]
	v_mfma_f32_16x16x32_bf16 v[136:139], v[108:111], v[172:175], v[136:139]
	v_mfma_f32_16x16x32_bf16 v[132:135], v[120:123], v[172:175], v[132:135]
	v_mfma_f32_16x16x32_bf16 v[86:89], v[108:111], v[180:183], v[86:89]
	v_mfma_f32_16x16x32_bf16 v[82:85], v[120:123], v[180:183], v[82:85]
	v_mfma_f32_16x16x32_bf16 v[70:73], v[108:111], v[188:191], v[70:73]
	v_mfma_f32_16x16x32_bf16 v[66:69], v[120:123], v[188:191], v[66:69]
	v_mfma_f32_16x16x32_bf16 v[152:155], v[112:115], v[168:171], v[152:155]
	v_mfma_f32_16x16x32_bf16 v[148:151], v[128:131], v[168:171], v[148:151]
	v_mfma_f32_16x16x32_bf16 v[136:139], v[112:115], v[176:179], v[136:139]
	v_mfma_f32_16x16x32_bf16 v[132:135], v[128:131], v[176:179], v[132:135]
	v_mfma_f32_16x16x32_bf16 v[86:89], v[112:115], v[184:187], v[86:89]
	v_mfma_f32_16x16x32_bf16 v[82:85], v[128:131], v[184:187], v[82:85]
	v_mfma_f32_16x16x32_bf16 v[70:73], v[112:115], v[192:195], v[70:73]
	v_mfma_f32_16x16x32_bf16 v[66:69], v[128:131], v[192:195], v[66:69]
	s_setprio 0
	s_barrier
	s_add_i32 s4, s6, s91
	v_lshl_add_u64 v[200:201], v[200:201], 0, s[42:43]
	s_mov_b32 m0, s4
	ds_read_b128 v[164:167], v241 offset:49152
	ds_read_b128 v[168:171], v241 offset:50176
	ds_read_b128 v[172:175], v241 offset:51200
	ds_read_b128 v[176:179], v241 offset:52224
	ds_read_b128 v[180:183], v241 offset:53248
	ds_read_b128 v[184:187], v241 offset:54272
	ds_read_b128 v[188:191], v241 offset:55296
	ds_read_b128 v[192:195], v241 offset:56320
	global_load_lds_dwordx4 v[200:201], off
	s_add_i32 m0, s4, 0x2000
	s_add_u32 s4, s70, 0x40080
	v_lshl_add_u64 v[200:201], v[202:203], 0, s[42:43]
	s_addc_u32 s5, s71, 0
	s_add_i32 s6, s7, s91
	global_load_lds_dwordx4 v[200:201], off
	v_lshl_add_u64 v[200:201], s[4:5], 0, v[204:205]
	s_mov_b32 m0, s6
	s_nop 0
	global_load_lds_dwordx4 v[200:201], off
	v_lshl_add_u64 v[200:201], s[4:5], 0, v[208:209]
	s_add_i32 m0, s6, 0x2000
	s_nop 0
	global_load_lds_dwordx4 v[200:201], off
	v_lshl_add_u64 v[200:201], v[210:211], 0, s[42:43]
	s_add_i32 m0, s44, 0x8000
	s_nop 0
	global_load_lds_dwordx4 v[200:201], off
	v_lshl_add_u64 v[200:201], v[212:213], 0, s[42:43]
	s_add_i32 m0, s44, 0xa000
	s_nop 0
	global_load_lds_dwordx4 v[200:201], off
	s_waitcnt vmcnt(8)
	s_waitcnt lgkmcnt(0)
	s_setprio 1
	s_barrier
	v_mfma_f32_16x16x32_bf16 v[62:65], v[90:93], v[164:167], v[62:65]
	v_mfma_f32_16x16x32_bf16 v[58:61], v[100:103], v[164:167], v[58:61]
	v_mfma_f32_16x16x32_bf16 v[46:49], v[90:93], v[172:175], v[46:49]
	v_mfma_f32_16x16x32_bf16 v[42:45], v[100:103], v[172:175], v[42:45]
	v_mfma_f32_16x16x32_bf16 v[30:33], v[90:93], v[180:183], v[30:33]
	v_mfma_f32_16x16x32_bf16 v[26:29], v[100:103], v[180:183], v[26:29]
	v_mfma_f32_16x16x32_bf16 v[14:17], v[90:93], v[188:191], v[14:17]
	v_mfma_f32_16x16x32_bf16 v[10:13], v[100:103], v[188:191], v[10:13]
	v_mfma_f32_16x16x32_bf16 v[62:65], v[94:97], v[168:171], v[62:65]
	v_mfma_f32_16x16x32_bf16 v[58:61], v[104:107], v[168:171], v[58:61]
	v_mfma_f32_16x16x32_bf16 v[46:49], v[94:97], v[176:179], v[46:49]
	v_mfma_f32_16x16x32_bf16 v[42:45], v[104:107], v[176:179], v[42:45]
	v_mfma_f32_16x16x32_bf16 v[30:33], v[94:97], v[184:187], v[30:33]
	v_mfma_f32_16x16x32_bf16 v[26:29], v[104:107], v[184:187], v[26:29]
	v_mfma_f32_16x16x32_bf16 v[14:17], v[94:97], v[192:195], v[14:17]
	v_mfma_f32_16x16x32_bf16 v[10:13], v[104:107], v[192:195], v[10:13]
	s_setprio 0
	s_setprio 1
	v_mfma_f32_16x16x32_bf16 v[54:57], v[108:111], v[164:167], v[54:57]
	v_mfma_f32_16x16x32_bf16 v[50:53], v[120:123], v[164:167], v[50:53]
	v_mfma_f32_16x16x32_bf16 v[38:41], v[108:111], v[172:175], v[38:41]
	v_mfma_f32_16x16x32_bf16 v[34:37], v[120:123], v[172:175], v[34:37]
	v_mfma_f32_16x16x32_bf16 v[22:25], v[108:111], v[180:183], v[22:25]
	v_mfma_f32_16x16x32_bf16 v[18:21], v[120:123], v[180:183], v[18:21]
	v_mfma_f32_16x16x32_bf16 v[6:9], v[108:111], v[188:191], v[6:9]
	v_mfma_f32_16x16x32_bf16 v[2:5], v[120:123], v[188:191], v[2:5]
	v_mfma_f32_16x16x32_bf16 v[54:57], v[112:115], v[168:171], v[54:57]
	v_mfma_f32_16x16x32_bf16 v[50:53], v[128:131], v[168:171], v[50:53]
	v_mfma_f32_16x16x32_bf16 v[38:41], v[112:115], v[176:179], v[38:41]
	v_mfma_f32_16x16x32_bf16 v[34:37], v[128:131], v[176:179], v[34:37]
	v_mfma_f32_16x16x32_bf16 v[22:25], v[112:115], v[184:187], v[22:25]
	v_mfma_f32_16x16x32_bf16 v[18:21], v[128:131], v[184:187], v[18:21]
	v_mfma_f32_16x16x32_bf16 v[6:9], v[112:115], v[192:195], v[6:9]
	v_mfma_f32_16x16x32_bf16 v[2:5], v[128:131], v[192:195], v[2:5]
	s_setprio 0
	s_barrier
	s_add_i32 s97, s97, 2
	s_add_u32 s68, s68, 0x100
	s_addc_u32 s69, s69, 0
	s_add_u32 vcc_hi, vcc_hi, 0x100
	s_addc_u32 s96, s96, 0
	s_cmp_gt_u32 s97, 13
	s_cbranch_scc0 .LBB0_864
	s_mov_b32 s100, 1
	s_and_b64 vcc, exec, s[12:13]
	s_cbranch_vccz .LBB0_867
	s_lshl_b32 s6, s94, 8
	s_add_i32 s5, s6, 0xffffc000
	s_lshr_b32 s5, s5, 12
	s_ashr_i32 s4, s94, 5
	s_add_i32 s5, s5, 2
	s_cmp_lt_i32 s94, 64
	s_cselect_b32 s4, s4, s5
	s_ashr_i32 s5, s4, 31
	s_lshl_b64 s[4:5], s[4:5], 14
	v_lshl_or_b32 v164, s18, 8, v240
	s_add_u32 s44, s79, s4
	s_addc_u32 s45, s88, s5
	v_ashrrev_i32_e32 v165, 31, v164
	v_add_u32_e32 v222, s6, v238
	s_add_u32 s4, s89, s4
	v_lshlrev_b64 v[210:211], 1, v[164:165]
	v_ashrrev_i32_e32 v223, 31, v222
	v_lshlrev_b64 v[90:91], 2, v[164:165]
	s_addc_u32 s5, s90, s5
	v_lshl_add_u64 v[164:165], s[82:83], 0, v[210:211]
	v_lshlrev_b64 v[226:227], 11, v[222:223]
	v_lshl_add_u64 v[92:93], s[44:45], 0, v[90:91]
	v_lshl_add_u64 v[94:95], s[4:5], 0, v[90:91]
	v_lshl_add_u64 v[166:167], v[164:165], 0, v[226:227]
	global_load_dwordx4 v[120:123], v[92:93], off offset:16
	global_load_dwordx4 v[128:131], v[92:93], off
	global_load_dwordx4 v[108:111], v[94:95], off offset:16
	global_load_dwordx4 v[112:115], v[94:95], off
	global_load_dwordx4 v[100:103], v[92:93], off offset:528
	global_load_dwordx4 v[104:107], v[92:93], off offset:512
	s_nop 0
	global_load_dwordx4 v[90:93], v[94:95], off offset:528
	s_nop 0
	global_load_dwordx4 v[94:97], v[94:95], off offset:512
	s_nop 0
	global_load_dwordx4 v[192:195], v[166:167], off
	global_load_dwordx4 v[188:191], v[166:167], off offset:256
	v_or_b32_e32 v220, 16, v222
	v_ashrrev_i32_e32 v221, 31, v220
	v_or_b32_e32 v216, 32, v222
	v_or_b32_e32 v212, 48, v222
	v_lshlrev_b64 v[224:225], 11, v[220:221]
	v_ashrrev_i32_e32 v217, 31, v216
	v_ashrrev_i32_e32 v213, 31, v212
	v_lshl_add_u64 v[166:167], v[164:165], 0, v[224:225]
	v_lshlrev_b64 v[218:219], 11, v[216:217]
	v_lshlrev_b64 v[214:215], 11, v[212:213]
	global_load_dwordx4 v[184:187], v[166:167], off
	global_load_dwordx4 v[180:183], v[166:167], off offset:256
	v_lshl_add_u64 v[166:167], v[164:165], 0, v[218:219]
	v_lshl_add_u64 v[164:165], v[164:165], 0, v[214:215]
	global_load_dwordx4 v[176:179], v[166:167], off
	global_load_dwordx4 v[172:175], v[166:167], off offset:256
	global_load_dwordx4 v[168:171], v[164:165], off
	s_nop 0
	global_load_dwordx4 v[164:167], v[164:165], off offset:256
	s_barrier
	s_branch .Lmy_g2a_afterload

.Lmy_g2a_afterload:
	v_and_b32_e32 v201, 64, v229
	v_xor_b32_e32 v200, 16, v229
	v_add_u32_e32 v201, 64, v201
	v_cmp_lt_i32_e32 vcc, v200, v201
	s_lshl_b32 s68, s18, 2
	s_ashr_i32 s69, s68, 31
	v_cndmask_b32_e32 v200, v229, v200, vcc
	v_lshlrev_b32_e32 v242, 2, v200
	v_xor_b32_e32 v200, 32, v229
	v_cmp_lt_i32_e32 vcc, v200, v201
	s_waitcnt vmcnt(0)
	v_and_b32_e32 v201, 0xffff0000, v192
	v_cndmask_b32_e32 v200, v229, v200, vcc
	s_andn2_b64 vcc, exec, s[40:41]
	v_lshlrev_b32_e32 v243, 2, v200
	v_lshlrev_b32_e32 v200, 16, v192
	v_lshlrev_b32_e32 v192, 16, v193
	v_and_b32_e32 v193, 0xffff0000, v193
	v_lshlrev_b32_e32 v202, 16, v194
	v_and_b32_e32 v203, 0xffff0000, v194
	v_lshlrev_b32_e32 v194, 16, v195
	v_and_b32_e32 v195, 0xffff0000, v195
	v_pk_fma_f32 v[162:163], v[162:163], v[130:131], v[192:193]
	v_pk_fma_f32 v[192:193], v[158:159], v[122:123], v[194:195]
	v_pk_fma_f32 v[194:195], v[156:157], v[120:121], v[202:203]
	v_pk_fma_f32 v[160:161], v[160:161], v[128:129], v[200:201]
	v_pk_mul_f32 v[156:157], v[194:195], v[194:195]
	v_pk_mul_f32 v[158:159], v[192:193], v[192:193]
	v_pk_fma_f32 v[156:157], v[160:161], v[160:161], v[156:157]
	v_pk_fma_f32 v[158:159], v[162:163], v[162:163], v[158:159]
	v_add_f32_e32 v156, v156, v157
	v_add_f32_e32 v157, v158, v159
	v_lshl_add_u64 v[200:201], s[82:83], 0, v[226:227]
	v_add_f32_e32 v202, v156, v157
	v_cvt_pk_bf16_f32 v156, v160, v161
	v_cvt_pk_bf16_f32 v157, v162, v163
	v_cvt_pk_bf16_f32 v158, v194, v195
	v_cvt_pk_bf16_f32 v159, v192, v193
	v_lshl_add_u64 v[200:201], v[200:201], 0, v[210:211]
	s_cbranch_vccnz .Lmy_wt_g2a_0
	global_store_dwordx4 v[200:201], v[156:159], off

.LBB0_908:
	s_add_u32 s4, s56, 0xfffc0080
	s_addc_u32 s5, s57, -1
	s_add_i32 s45, 0, 0x10000
	s_cmp_eq_u32 s96, 12
	s_cselect_b32 s71, s21, s5
	s_cselect_b32 s70, s93, s4
	s_cselect_b32 s69, s15, vcc_lo
	s_cselect_b32 s68, s94, s95
	s_add_i32 s97, 0, 0x14000
	v_add_u32_e32 v104, s45, v223
	v_add_u32_e32 v124, s97, v223
	ds_read_b128 v[86:89], v104
	ds_read_b128 v[90:93], v104 offset:1024
	ds_read_b128 v[100:103], v104 offset:2048
	ds_read_b128 v[104:107], v104 offset:3072
	ds_read_b128 v[108:111], v124
	ds_read_b128 v[112:115], v124 offset:1024
	ds_read_b128 v[116:119], v124 offset:2048
	ds_read_b128 v[124:127], v124 offset:3072
	s_add_i32 s44, s74, 0
	v_lshl_add_u64 v[200:201], s[56:57], 0, v[98:99]
	s_add_i32 m0, s44, 0xc000
	ds_read_b128 v[164:167], v225
	ds_read_b128 v[168:171], v225 offset:1024
	ds_read_b128 v[172:175], v225 offset:2048
	ds_read_b128 v[176:179], v225 offset:3072
	ds_read_b128 v[180:183], v225 offset:4096
	ds_read_b128 v[184:187], v225 offset:5120
	ds_read_b128 v[188:191], v225 offset:6144
	ds_read_b128 v[192:195], v225 offset:7168
	global_load_lds_dwordx4 v[200:201], off
	v_lshl_add_u64 v[200:201], s[56:57], 0, v[206:207]
	s_add_i32 m0, s44, 0xe000
	s_nop 0
	global_load_lds_dwordx4 v[200:201], off
	s_waitcnt vmcnt(8)
	s_waitcnt lgkmcnt(0)
	s_setprio 1
	s_barrier
	v_mfma_f32_16x16x32_bf16 v[160:163], v[86:89], v[164:167], v[160:163]
	v_mfma_f32_16x16x32_bf16 v[156:159], v[100:103], v[164:167], v[156:159]
	v_mfma_f32_16x16x32_bf16 v[144:147], v[86:89], v[172:175], v[144:147]
	v_mfma_f32_16x16x32_bf16 v[140:143], v[100:103], v[172:175], v[140:143]
	v_mfma_f32_16x16x32_bf16 v[128:131], v[86:89], v[180:183], v[128:131]
	v_mfma_f32_16x16x32_bf16 v[120:123], v[100:103], v[180:183], v[120:123]
	v_mfma_f32_16x16x32_bf16 v[78:81], v[86:89], v[188:191], v[78:81]
	v_mfma_f32_16x16x32_bf16 v[74:77], v[100:103], v[188:191], v[74:77]
	v_mfma_f32_16x16x32_bf16 v[160:163], v[90:93], v[168:171], v[160:163]
	v_mfma_f32_16x16x32_bf16 v[156:159], v[104:107], v[168:171], v[156:159]
	v_mfma_f32_16x16x32_bf16 v[144:147], v[90:93], v[176:179], v[144:147]
	v_mfma_f32_16x16x32_bf16 v[140:143], v[104:107], v[176:179], v[140:143]
	v_mfma_f32_16x16x32_bf16 v[128:131], v[90:93], v[184:187], v[128:131]
	v_mfma_f32_16x16x32_bf16 v[120:123], v[104:107], v[184:187], v[120:123]
	v_mfma_f32_16x16x32_bf16 v[78:81], v[90:93], v[192:195], v[78:81]
	v_mfma_f32_16x16x32_bf16 v[74:77], v[104:107], v[192:195], v[74:77]
	s_setprio 0
	s_setprio 1
	v_mfma_f32_16x16x32_bf16 v[152:155], v[108:111], v[164:167], v[152:155]
	v_mfma_f32_16x16x32_bf16 v[148:151], v[116:119], v[164:167], v[148:151]
	v_mfma_f32_16x16x32_bf16 v[136:139], v[108:111], v[172:175], v[136:139]
	v_mfma_f32_16x16x32_bf16 v[132:135], v[116:119], v[172:175], v[132:135]
	v_mfma_f32_16x16x32_bf16 v[94:97], v[108:111], v[180:183], v[94:97]
	v_mfma_f32_16x16x32_bf16 v[82:85], v[116:119], v[180:183], v[82:85]
	v_mfma_f32_16x16x32_bf16 v[70:73], v[108:111], v[188:191], v[70:73]
	v_mfma_f32_16x16x32_bf16 v[66:69], v[116:119], v[188:191], v[66:69]
	v_mfma_f32_16x16x32_bf16 v[152:155], v[112:115], v[168:171], v[152:155]
	v_mfma_f32_16x16x32_bf16 v[148:151], v[124:127], v[168:171], v[148:151]
	v_mfma_f32_16x16x32_bf16 v[136:139], v[112:115], v[176:179], v[136:139]
	v_mfma_f32_16x16x32_bf16 v[132:135], v[124:127], v[176:179], v[132:135]
	v_mfma_f32_16x16x32_bf16 v[94:97], v[112:115], v[184:187], v[94:97]
	v_mfma_f32_16x16x32_bf16 v[82:85], v[124:127], v[184:187], v[82:85]
	v_mfma_f32_16x16x32_bf16 v[70:73], v[112:115], v[192:195], v[70:73]
	v_mfma_f32_16x16x32_bf16 v[66:69], v[124:127], v[192:195], v[66:69]
	s_setprio 0
	s_barrier
	s_add_i32 s4, s45, s74
	v_lshl_add_u64 v[200:201], s[68:69], 0, v[204:205]
	s_mov_b32 m0, s4
	ds_read_b128 v[164:167], v225 offset:16384
	ds_read_b128 v[168:171], v225 offset:17408
	ds_read_b128 v[172:175], v225 offset:18432
	ds_read_b128 v[176:179], v225 offset:19456
	ds_read_b128 v[180:183], v225 offset:20480
	ds_read_b128 v[184:187], v225 offset:21504
	ds_read_b128 v[188:191], v225 offset:22528
	ds_read_b128 v[192:195], v225 offset:23552
	global_load_lds_dwordx4 v[200:201], off
	s_add_i32 m0, s4, 0x2000
	s_add_u32 s4, s68, 0x40000
	v_lshl_add_u64 v[202:203], s[68:69], 0, v[208:209]
	s_addc_u32 s5, s69, 0
	s_add_i32 s45, s97, s74
	global_load_lds_dwordx4 v[202:203], off
	v_lshl_add_u64 v[210:211], s[4:5], 0, v[204:205]
	s_mov_b32 m0, s45
	v_lshl_add_u64 v[212:213], s[70:71], 0, v[206:207]
	global_load_lds_dwordx4 v[210:211], off
	v_lshl_add_u64 v[210:211], s[4:5], 0, v[208:209]
	s_add_i32 m0, s45, 0x2000
	s_nop 0
	global_load_lds_dwordx4 v[210:211], off
	v_lshl_add_u64 v[210:211], s[70:71], 0, v[98:99]
	s_mov_b32 m0, s44
	s_nop 0
	global_load_lds_dwordx4 v[210:211], off
	s_add_i32 m0, s44, 0x2000
	s_nop 0
	global_load_lds_dwordx4 v[212:213], off
	s_waitcnt vmcnt(8)
	s_waitcnt lgkmcnt(0)
	s_setprio 1
	s_barrier
	v_mfma_f32_16x16x32_bf16 v[62:65], v[86:89], v[164:167], v[62:65]
	v_mfma_f32_16x16x32_bf16 v[58:61], v[100:103], v[164:167], v[58:61]
	v_mfma_f32_16x16x32_bf16 v[46:49], v[86:89], v[172:175], v[46:49]
	v_mfma_f32_16x16x32_bf16 v[42:45], v[100:103], v[172:175], v[42:45]
	v_mfma_f32_16x16x32_bf16 v[30:33], v[86:89], v[180:183], v[30:33]
	v_mfma_f32_16x16x32_bf16 v[26:29], v[100:103], v[180:183], v[26:29]
	v_mfma_f32_16x16x32_bf16 v[14:17], v[86:89], v[188:191], v[14:17]
	v_mfma_f32_16x16x32_bf16 v[10:13], v[100:103], v[188:191], v[10:13]
	v_mfma_f32_16x16x32_bf16 v[62:65], v[90:93], v[168:171], v[62:65]
	v_mfma_f32_16x16x32_bf16 v[58:61], v[104:107], v[168:171], v[58:61]
	v_mfma_f32_16x16x32_bf16 v[46:49], v[90:93], v[176:179], v[46:49]
	v_mfma_f32_16x16x32_bf16 v[42:45], v[104:107], v[176:179], v[42:45]
	v_mfma_f32_16x16x32_bf16 v[30:33], v[90:93], v[184:187], v[30:33]
	v_mfma_f32_16x16x32_bf16 v[26:29], v[104:107], v[184:187], v[26:29]
	v_mfma_f32_16x16x32_bf16 v[14:17], v[90:93], v[192:195], v[14:17]
	v_mfma_f32_16x16x32_bf16 v[10:13], v[104:107], v[192:195], v[10:13]
	s_setprio 0
	s_setprio 1
	v_mfma_f32_16x16x32_bf16 v[54:57], v[108:111], v[164:167], v[54:57]
	v_mfma_f32_16x16x32_bf16 v[50:53], v[116:119], v[164:167], v[50:53]
	v_mfma_f32_16x16x32_bf16 v[38:41], v[108:111], v[172:175], v[38:41]
	v_mfma_f32_16x16x32_bf16 v[34:37], v[116:119], v[172:175], v[34:37]
	v_mfma_f32_16x16x32_bf16 v[22:25], v[108:111], v[180:183], v[22:25]
	v_mfma_f32_16x16x32_bf16 v[18:21], v[116:119], v[180:183], v[18:21]
	v_mfma_f32_16x16x32_bf16 v[6:9], v[108:111], v[188:191], v[6:9]
	v_mfma_f32_16x16x32_bf16 v[2:5], v[116:119], v[188:191], v[2:5]
	v_mfma_f32_16x16x32_bf16 v[54:57], v[112:115], v[168:171], v[54:57]
	v_mfma_f32_16x16x32_bf16 v[50:53], v[124:127], v[168:171], v[50:53]
	v_mfma_f32_16x16x32_bf16 v[38:41], v[112:115], v[176:179], v[38:41]
	v_mfma_f32_16x16x32_bf16 v[34:37], v[124:127], v[176:179], v[34:37]
	v_mfma_f32_16x16x32_bf16 v[22:25], v[112:115], v[184:187], v[22:25]
	v_mfma_f32_16x16x32_bf16 v[18:21], v[124:127], v[184:187], v[18:21]
	v_mfma_f32_16x16x32_bf16 v[6:9], v[112:115], v[192:195], v[6:9]
	v_mfma_f32_16x16x32_bf16 v[2:5], v[124:127], v[192:195], v[2:5]
	s_setprio 0
	s_barrier
	s_add_i32 s45, 0, 0x18000
	s_add_i32 s97, 0, 0x1c000
	v_add_u32_e32 v104, s45, v223
	v_add_u32_e32 v124, s97, v223
	ds_read_b128 v[86:89], v104
	ds_read_b128 v[90:93], v104 offset:1024
	ds_read_b128 v[100:103], v104 offset:2048
	ds_read_b128 v[104:107], v104 offset:3072
	ds_read_b128 v[108:111], v124
	ds_read_b128 v[112:115], v124 offset:1024
	ds_read_b128 v[116:119], v124 offset:2048
	ds_read_b128 v[124:127], v124 offset:3072
	s_add_u32 s4, s70, 0x40000
	s_addc_u32 s5, s71, 0
	v_lshl_add_u64 v[214:215], s[4:5], 0, v[98:99]
	s_add_i32 m0, s44, 0x4000
	ds_read_b128 v[164:167], v225 offset:32768
	ds_read_b128 v[168:171], v225 offset:33792
	ds_read_b128 v[172:175], v225 offset:34816
	ds_read_b128 v[176:179], v225 offset:35840
	ds_read_b128 v[180:183], v225 offset:36864
	ds_read_b128 v[184:187], v225 offset:37888
	ds_read_b128 v[188:191], v225 offset:38912
	ds_read_b128 v[192:195], v225 offset:39936
	global_load_lds_dwordx4 v[214:215], off
	v_lshl_add_u64 v[214:215], s[4:5], 0, v[206:207]
	s_add_i32 m0, s44, 0x6000
	s_nop 0
	global_load_lds_dwordx4 v[214:215], off
	s_waitcnt vmcnt(8)
	s_waitcnt lgkmcnt(0)
	s_setprio 1
	s_barrier
	v_mfma_f32_16x16x32_bf16 v[160:163], v[86:89], v[164:167], v[160:163]
	v_mfma_f32_16x16x32_bf16 v[156:159], v[100:103], v[164:167], v[156:159]
	v_mfma_f32_16x16x32_bf16 v[144:147], v[86:89], v[172:175], v[144:147]
	v_mfma_f32_16x16x32_bf16 v[140:143], v[100:103], v[172:175], v[140:143]
	v_mfma_f32_16x16x32_bf16 v[128:131], v[86:89], v[180:183], v[128:131]
	v_mfma_f32_16x16x32_bf16 v[120:123], v[100:103], v[180:183], v[120:123]
	v_mfma_f32_16x16x32_bf16 v[78:81], v[86:89], v[188:191], v[78:81]
	v_mfma_f32_16x16x32_bf16 v[74:77], v[100:103], v[188:191], v[74:77]
	v_mfma_f32_16x16x32_bf16 v[160:163], v[90:93], v[168:171], v[160:163]
	v_mfma_f32_16x16x32_bf16 v[156:159], v[104:107], v[168:171], v[156:159]
	v_mfma_f32_16x16x32_bf16 v[144:147], v[90:93], v[176:179], v[144:147]
	v_mfma_f32_16x16x32_bf16 v[140:143], v[104:107], v[176:179], v[140:143]
	v_mfma_f32_16x16x32_bf16 v[128:131], v[90:93], v[184:187], v[128:131]
	v_mfma_f32_16x16x32_bf16 v[120:123], v[104:107], v[184:187], v[120:123]
	v_mfma_f32_16x16x32_bf16 v[78:81], v[90:93], v[192:195], v[78:81]
	v_mfma_f32_16x16x32_bf16 v[74:77], v[104:107], v[192:195], v[74:77]
	s_setprio 0
	s_setprio 1
	v_mfma_f32_16x16x32_bf16 v[152:155], v[108:111], v[164:167], v[152:155]
	v_mfma_f32_16x16x32_bf16 v[148:151], v[116:119], v[164:167], v[148:151]
	v_mfma_f32_16x16x32_bf16 v[136:139], v[108:111], v[172:175], v[136:139]
	v_mfma_f32_16x16x32_bf16 v[132:135], v[116:119], v[172:175], v[132:135]
	v_mfma_f32_16x16x32_bf16 v[94:97], v[108:111], v[180:183], v[94:97]
	v_mfma_f32_16x16x32_bf16 v[82:85], v[116:119], v[180:183], v[82:85]
	v_mfma_f32_16x16x32_bf16 v[70:73], v[108:111], v[188:191], v[70:73]
	v_mfma_f32_16x16x32_bf16 v[66:69], v[116:119], v[188:191], v[66:69]
	v_mfma_f32_16x16x32_bf16 v[152:155], v[112:115], v[168:171], v[152:155]
	v_mfma_f32_16x16x32_bf16 v[148:151], v[124:127], v[168:171], v[148:151]
	v_mfma_f32_16x16x32_bf16 v[136:139], v[112:115], v[176:179], v[136:139]
	v_mfma_f32_16x16x32_bf16 v[132:135], v[124:127], v[176:179], v[132:135]
	v_mfma_f32_16x16x32_bf16 v[94:97], v[112:115], v[184:187], v[94:97]
	v_mfma_f32_16x16x32_bf16 v[82:85], v[124:127], v[184:187], v[82:85]
	v_mfma_f32_16x16x32_bf16 v[70:73], v[112:115], v[192:195], v[70:73]
	v_mfma_f32_16x16x32_bf16 v[66:69], v[124:127], v[192:195], v[66:69]
	s_setprio 0
	s_barrier
	s_add_i32 s4, s45, s74
	v_lshl_add_u64 v[200:201], v[200:201], 0, s[42:43]
	s_mov_b32 m0, s4
	ds_read_b128 v[164:167], v225 offset:49152
	ds_read_b128 v[168:171], v225 offset:50176
	ds_read_b128 v[172:175], v225 offset:51200
	ds_read_b128 v[176:179], v225 offset:52224
	ds_read_b128 v[180:183], v225 offset:53248
	ds_read_b128 v[184:187], v225 offset:54272
	ds_read_b128 v[188:191], v225 offset:55296
	ds_read_b128 v[192:195], v225 offset:56320
	global_load_lds_dwordx4 v[200:201], off
	s_add_i32 m0, s4, 0x2000
	s_add_u32 s4, s68, 0x40080
	v_lshl_add_u64 v[200:201], v[202:203], 0, s[42:43]
	s_addc_u32 s5, s69, 0
	s_add_i32 s45, s97, s74
	global_load_lds_dwordx4 v[200:201], off
	v_lshl_add_u64 v[200:201], s[4:5], 0, v[204:205]
	s_mov_b32 m0, s45
	s_nop 0
	global_load_lds_dwordx4 v[200:201], off
	v_lshl_add_u64 v[200:201], s[4:5], 0, v[208:209]
	s_add_i32 m0, s45, 0x2000
	s_nop 0
	global_load_lds_dwordx4 v[200:201], off
	v_lshl_add_u64 v[200:201], v[210:211], 0, s[42:43]
	s_add_i32 m0, s44, 0x8000
	s_nop 0
	global_load_lds_dwordx4 v[200:201], off
	v_lshl_add_u64 v[200:201], v[212:213], 0, s[42:43]
	s_add_i32 m0, s44, 0xa000
	s_nop 0
	global_load_lds_dwordx4 v[200:201], off
	s_waitcnt vmcnt(8)
	s_waitcnt lgkmcnt(0)
	s_setprio 1
	s_barrier
	v_mfma_f32_16x16x32_bf16 v[62:65], v[86:89], v[164:167], v[62:65]
	v_mfma_f32_16x16x32_bf16 v[58:61], v[100:103], v[164:167], v[58:61]
	v_mfma_f32_16x16x32_bf16 v[46:49], v[86:89], v[172:175], v[46:49]
	v_mfma_f32_16x16x32_bf16 v[42:45], v[100:103], v[172:175], v[42:45]
	v_mfma_f32_16x16x32_bf16 v[30:33], v[86:89], v[180:183], v[30:33]
	v_mfma_f32_16x16x32_bf16 v[26:29], v[100:103], v[180:183], v[26:29]
	v_mfma_f32_16x16x32_bf16 v[14:17], v[86:89], v[188:191], v[14:17]
	v_mfma_f32_16x16x32_bf16 v[10:13], v[100:103], v[188:191], v[10:13]
	v_mfma_f32_16x16x32_bf16 v[62:65], v[90:93], v[168:171], v[62:65]
	v_mfma_f32_16x16x32_bf16 v[58:61], v[104:107], v[168:171], v[58:61]
	v_mfma_f32_16x16x32_bf16 v[46:49], v[90:93], v[176:179], v[46:49]
	v_mfma_f32_16x16x32_bf16 v[42:45], v[104:107], v[176:179], v[42:45]
	v_mfma_f32_16x16x32_bf16 v[30:33], v[90:93], v[184:187], v[30:33]
	v_mfma_f32_16x16x32_bf16 v[26:29], v[104:107], v[184:187], v[26:29]
	v_mfma_f32_16x16x32_bf16 v[14:17], v[90:93], v[192:195], v[14:17]
	v_mfma_f32_16x16x32_bf16 v[10:13], v[104:107], v[192:195], v[10:13]
	s_setprio 0
	s_setprio 1
	v_mfma_f32_16x16x32_bf16 v[54:57], v[108:111], v[164:167], v[54:57]
	v_mfma_f32_16x16x32_bf16 v[50:53], v[116:119], v[164:167], v[50:53]
	v_mfma_f32_16x16x32_bf16 v[38:41], v[108:111], v[172:175], v[38:41]
	v_mfma_f32_16x16x32_bf16 v[34:37], v[116:119], v[172:175], v[34:37]
	v_mfma_f32_16x16x32_bf16 v[22:25], v[108:111], v[180:183], v[22:25]
	v_mfma_f32_16x16x32_bf16 v[18:21], v[116:119], v[180:183], v[18:21]
	v_mfma_f32_16x16x32_bf16 v[6:9], v[108:111], v[188:191], v[6:9]
	v_mfma_f32_16x16x32_bf16 v[2:5], v[116:119], v[188:191], v[2:5]
	v_mfma_f32_16x16x32_bf16 v[54:57], v[112:115], v[168:171], v[54:57]
	v_mfma_f32_16x16x32_bf16 v[50:53], v[124:127], v[168:171], v[50:53]
	v_mfma_f32_16x16x32_bf16 v[38:41], v[112:115], v[176:179], v[38:41]
	v_mfma_f32_16x16x32_bf16 v[34:37], v[124:127], v[176:179], v[34:37]
	v_mfma_f32_16x16x32_bf16 v[22:25], v[112:115], v[184:187], v[22:25]
	v_mfma_f32_16x16x32_bf16 v[18:21], v[124:127], v[184:187], v[18:21]
	v_mfma_f32_16x16x32_bf16 v[6:9], v[112:115], v[192:195], v[6:9]
	v_mfma_f32_16x16x32_bf16 v[2:5], v[124:127], v[192:195], v[2:5]
	s_setprio 0
	s_barrier
	s_add_i32 s96, s96, 2
	s_add_u32 s56, s56, 0x100
	s_addc_u32 s57, s57, 0
	s_add_u32 s95, s95, 0x100
	s_addc_u32 vcc_lo, vcc_lo, 0
	s_cmp_gt_u32 s96, 13
	s_cbranch_scc0 .LBB0_908
	s_mov_b32 s100, 1
	v_mov_b32_e32 v196, 0x2d00
	v_mov_b32_e32 v231, 0x2400
	v_mov_b32_e32 v228, 0x1b00
	s_and_b64 vcc, exec, s[0:1]
	s_movk_i32 s21, 0x4000
	s_cbranch_vccz .LBB0_911
	s_lshl_b32 s15, s92, 8
	s_add_i32 s5, s15, 0xffffc000
	s_lshr_b32 s5, s5, 12
	s_ashr_i32 s4, s92, 5
	s_add_i32 s5, s5, 2
	s_cmp_lt_i32 s92, 64
	v_add_u32_e32 v214, s15, v222
	v_readlane_b32 s56, v252, 3
	s_cselect_b32 s4, s4, s5
	v_add_u32_e32 v88, 0xffffc000, v214
	v_ashrrev_i32_e32 v215, 31, v214
	v_cmp_gt_i32_e32 vcc, s21, v214
	v_readlane_b32 s57, v252, 4
	v_readlane_b32 s58, v252, 5
	v_readlane_b32 s59, v252, 6
	v_lshl_or_b32 v212, s18, 8, v224
	s_ashr_i32 s5, s4, 31
	v_cndmask_b32_e32 v89, 0, v215, vcc
	v_cndmask_b32_e32 v88, v88, v214, vcc
	v_mov_b32_e32 v170, s59
	v_mov_b32_e32 v171, s57
	v_mov_b32_e32 v172, s58
	v_mov_b32_e32 v173, s56
	s_lshl_b64 s[4:5], s[4:5], 14
	v_ashrrev_i32_e32 v213, 31, v212
	v_cndmask_b32_e32 v91, v170, v171, vcc
	v_cndmask_b32_e32 v90, v172, v173, vcc
	v_lshlrev_b64 v[88:89], 12, v[88:89]
	s_add_u32 s44, s79, s4
	v_lshlrev_b64 v[164:165], 2, v[212:213]
	v_lshl_add_u64 v[88:89], v[90:91], 0, v[88:89]
	s_addc_u32 s45, s88, s5
	v_lshl_add_u64 v[166:167], v[88:89], 0, v[164:165]
	v_lshl_add_u64 v[86:87], s[44:45], 0, v[164:165]
	global_load_dwordx4 v[238:241], v[166:167], off
	global_load_dwordx4 v[124:127], v[86:87], off
	global_load_dwordx4 v[116:119], v[86:87], off offset:16
	global_load_dwordx4 v[242:245], v[166:167], off offset:16
	s_add_u32 s4, s89, s4
	s_addc_u32 s5, s90, s5
	v_lshl_add_u64 v[90:91], s[4:5], 0, v[164:165]
	global_load_dwordx4 v[112:115], v[90:91], off
	global_load_dwordx4 v[108:111], v[90:91], off offset:16
	global_load_dwordx4 v[100:103], v[86:87], off offset:528
	global_load_dwordx4 v[104:107], v[86:87], off offset:512
	s_nop 0
	global_load_dwordx4 v[86:89], v[90:91], off offset:528
	s_nop 0
	global_load_dwordx4 v[90:93], v[90:91], off offset:512
	s_nop 0
	global_load_dwordx4 v[246:249], v[166:167], off offset:528
	global_load_dwordx4 v[200:203], v[166:167], off offset:512
	v_or_b32_e32 v220, 16, v214
	v_ashrrev_i32_e32 v221, 31, v220
	v_add_u32_e32 v166, 0xffffc010, v214
	v_cmp_gt_i32_e32 vcc, s21, v220
	v_or_b32_e32 v216, 32, v214
	v_ashrrev_i32_e32 v217, 31, v216
	v_cndmask_b32_e32 v167, 0, v221, vcc
	v_cndmask_b32_e32 v166, v166, v220, vcc
	v_cndmask_b32_e32 v169, v170, v171, vcc
	v_cndmask_b32_e32 v168, v172, v173, vcc
	v_lshlrev_b64 v[166:167], 12, v[166:167]
	v_lshl_add_u64 v[166:167], v[168:169], 0, v[166:167]
	v_lshl_add_u64 v[166:167], v[166:167], 0, v[164:165]
	global_load_dwordx4 v[188:191], v[166:167], off offset:16
	global_load_dwordx4 v[192:195], v[166:167], off
	global_load_dwordx4 v[180:183], v[166:167], off offset:528
	global_load_dwordx4 v[184:187], v[166:167], off offset:512
	v_add_u32_e32 v166, 0xffffc020, v214
	v_cmp_gt_i32_e32 vcc, s21, v216
	v_and_b32_e32 v211, 64, v229
	v_xor_b32_e32 v210, 16, v229
	v_cndmask_b32_e32 v167, 0, v217, vcc
	v_cndmask_b32_e32 v166, v166, v216, vcc
	v_cndmask_b32_e32 v169, v170, v171, vcc
	v_cndmask_b32_e32 v168, v172, v173, vcc
	v_lshlrev_b64 v[166:167], 12, v[166:167]
	v_lshl_add_u64 v[166:167], v[168:169], 0, v[166:167]
	v_lshl_add_u64 v[168:169], v[166:167], 0, v[164:165]
	global_load_dwordx4 v[172:175], v[168:169], off offset:16
	global_load_dwordx4 v[176:179], v[168:169], off
	global_load_dwordx4 v[164:167], v[168:169], off offset:528
	s_nop 0
	global_load_dwordx4 v[168:171], v[168:169], off offset:512
	s_barrier
	s_branch .Lmy_g2b_afterload

.Lmy_g2b_afterload:
	v_add_u32_e32 v211, 64, v211
	v_xor_b32_e32 v218, 32, v229
	v_cmp_lt_i32_e32 vcc, v210, v211
	s_lshl_b32 s56, s18, 2
	v_readlane_b32 s68, v252, 15
	v_cndmask_b32_e32 v210, v229, v210, vcc
	v_cmp_lt_i32_e32 vcc, v218, v211
	v_lshlrev_b32_e32 v227, 2, v210
	v_readlane_b32 s69, v252, 16
	v_cndmask_b32_e32 v211, v229, v218, vcc
	v_lshlrev_b32_e32 v226, 2, v211
	v_lshlrev_b64 v[210:211], 1, v[212:213]
	s_ashr_i32 s57, s56, 31
	v_readlane_b32 s60, v252, 7
	v_readlane_b32 s61, v252, 8
	v_readlane_b32 s62, v252, 9
	v_readlane_b32 s63, v252, 10
	v_readlane_b32 s64, v252, 11
	v_readlane_b32 s65, v252, 12
	v_readlane_b32 s66, v252, 13
	v_readlane_b32 s67, v252, 14
	v_readlane_b32 s70, v252, 17
	v_readlane_b32 s71, v252, 18
	s_waitcnt vmcnt(0)
	v_pk_fma_f32 v[160:161], v[160:161], v[124:125], v[238:239]
	v_pk_fma_f32 v[162:163], v[162:163], v[126:127], v[240:241]
	v_pk_fma_f32 v[218:219], v[158:159], v[118:119], v[244:245]
	v_pk_fma_f32 v[238:239], v[156:157], v[116:117], v[242:243]
	v_pk_mul_f32 v[156:157], v[218:219], v[218:219]
	v_pk_mul_f32 v[158:159], v[238:239], v[238:239]
	v_pk_fma_f32 v[156:157], v[162:163], v[162:163], v[156:157]
	v_pk_fma_f32 v[158:159], v[160:161], v[160:161], v[158:159]
	v_lshlrev_b64 v[240:241], 11, v[214:215]
	v_add_f32_e32 v158, v158, v159
	v_add_f32_e32 v156, v156, v157
	v_lshl_add_u64 v[242:243], s[82:83], 0, v[240:241]
	v_add_f32_e32 v244, v158, v156
	v_cvt_pk_bf16_f32 v156, v160, v161
	v_cvt_pk_bf16_f32 v157, v162, v163
	v_cvt_pk_bf16_f32 v158, v238, v239
	v_cvt_pk_bf16_f32 v159, v218, v219
	v_lshl_add_u64 v[242:243], v[242:243], 0, v[210:211]
	s_andn2_b64 vcc, exec, s[38:39]
	s_cbranch_vccnz .Lmy_wt_g2b_0
	global_store_dwordx4 v[242:243], v[156:159], off

.LBB0_1116:
	s_add_u32 s4, s74, 0xfff00080
	s_addc_u32 s5, s75, -1
	s_add_i32 s6, 0, 0x10000
	s_cmp_eq_u32 s95, 60
	s_cselect_b32 vcc_hi, s18, s5
	s_cselect_b32 vcc_lo, s21, s4
	s_cselect_b32 s79, s27, s94
	s_cselect_b32 s78, s69, s71
	s_add_i32 s7, 0, 0x14000
	v_add_u32_e32 v128, s6, v205
	v_add_u32_e32 v160, s7, v205
	ds_read_b128 v[112:115], v128
	ds_read_b128 v[116:119], v128 offset:1024
	ds_read_b128 v[124:127], v128 offset:2048
	ds_read_b128 v[128:131], v128 offset:3072
	ds_read_b128 v[148:151], v160
	ds_read_b128 v[152:155], v160 offset:1024
	ds_read_b128 v[156:159], v160 offset:2048
	ds_read_b128 v[160:163], v160 offset:3072
	s_add_i32 s44, s91, 0
	v_lshl_add_u64 v[194:195], s[74:75], 0, v[98:99]
	s_add_i32 m0, s44, 0xc000
	ds_read_b128 v[164:167], v207
	ds_read_b128 v[168:171], v207 offset:1024
	ds_read_b128 v[178:181], v207 offset:2048
	ds_read_b128 v[182:185], v207 offset:3072
	ds_read_b128 v[186:189], v207 offset:4096
	ds_read_b128 v[190:193], v207 offset:5120
	ds_read_b128 v[200:203], v207 offset:6144
	ds_read_b128 v[208:211], v207 offset:7168
	global_load_lds_dwordx4 v[194:195], off
	v_lshl_add_u64 v[194:195], s[74:75], 0, v[174:175]
	s_add_i32 m0, s44, 0xe000
	s_nop 0
	global_load_lds_dwordx4 v[194:195], off
	s_waitcnt vmcnt(8)
	s_waitcnt lgkmcnt(0)
	s_setprio 1
	s_barrier
	v_mfma_f32_16x16x32_bf16 v[144:147], v[112:115], v[164:167], v[144:147]
	v_mfma_f32_16x16x32_bf16 v[140:143], v[124:127], v[164:167], v[140:143]
	v_mfma_f32_16x16x32_bf16 v[120:123], v[112:115], v[178:181], v[120:123]
	v_mfma_f32_16x16x32_bf16 v[108:111], v[124:127], v[178:181], v[108:111]
	v_mfma_f32_16x16x32_bf16 v[94:97], v[112:115], v[186:189], v[94:97]
	v_mfma_f32_16x16x32_bf16 v[90:93], v[124:127], v[186:189], v[90:93]
	v_mfma_f32_16x16x32_bf16 v[78:81], v[112:115], v[200:203], v[78:81]
	v_mfma_f32_16x16x32_bf16 v[74:77], v[124:127], v[200:203], v[74:77]
	v_mfma_f32_16x16x32_bf16 v[144:147], v[116:119], v[168:171], v[144:147]
	v_mfma_f32_16x16x32_bf16 v[140:143], v[128:131], v[168:171], v[140:143]
	v_mfma_f32_16x16x32_bf16 v[120:123], v[116:119], v[182:185], v[120:123]
	v_mfma_f32_16x16x32_bf16 v[108:111], v[128:131], v[182:185], v[108:111]
	v_mfma_f32_16x16x32_bf16 v[94:97], v[116:119], v[190:193], v[94:97]
	v_mfma_f32_16x16x32_bf16 v[90:93], v[128:131], v[190:193], v[90:93]
	v_mfma_f32_16x16x32_bf16 v[78:81], v[116:119], v[208:211], v[78:81]
	v_mfma_f32_16x16x32_bf16 v[74:77], v[128:131], v[208:211], v[74:77]
	s_setprio 0
	s_setprio 1
	v_mfma_f32_16x16x32_bf16 v[136:139], v[148:151], v[164:167], v[136:139]
	v_mfma_f32_16x16x32_bf16 v[132:135], v[156:159], v[164:167], v[132:135]
	v_mfma_f32_16x16x32_bf16 v[104:107], v[148:151], v[178:181], v[104:107]
	v_mfma_f32_16x16x32_bf16 v[100:103], v[156:159], v[178:181], v[100:103]
	v_mfma_f32_16x16x32_bf16 v[86:89], v[148:151], v[186:189], v[86:89]
	v_mfma_f32_16x16x32_bf16 v[82:85], v[156:159], v[186:189], v[82:85]
	v_mfma_f32_16x16x32_bf16 v[70:73], v[148:151], v[200:203], v[70:73]
	v_mfma_f32_16x16x32_bf16 v[66:69], v[156:159], v[200:203], v[66:69]
	v_mfma_f32_16x16x32_bf16 v[136:139], v[152:155], v[168:171], v[136:139]
	v_mfma_f32_16x16x32_bf16 v[132:135], v[160:163], v[168:171], v[132:135]
	v_mfma_f32_16x16x32_bf16 v[104:107], v[152:155], v[182:185], v[104:107]
	v_mfma_f32_16x16x32_bf16 v[100:103], v[160:163], v[182:185], v[100:103]
	v_mfma_f32_16x16x32_bf16 v[86:89], v[152:155], v[190:193], v[86:89]
	v_mfma_f32_16x16x32_bf16 v[82:85], v[160:163], v[190:193], v[82:85]
	v_mfma_f32_16x16x32_bf16 v[70:73], v[152:155], v[208:211], v[70:73]
	v_mfma_f32_16x16x32_bf16 v[66:69], v[160:163], v[208:211], v[66:69]
	s_setprio 0
	s_barrier
	s_add_i32 s4, s6, s91
	v_lshl_add_u64 v[194:195], s[78:79], 0, v[172:173]
	s_mov_b32 m0, s4
	ds_read_b128 v[164:167], v207 offset:16384
	ds_read_b128 v[168:171], v207 offset:17408
	ds_read_b128 v[178:181], v207 offset:18432
	ds_read_b128 v[182:185], v207 offset:19456
	ds_read_b128 v[186:189], v207 offset:20480
	ds_read_b128 v[190:193], v207 offset:21504
	ds_read_b128 v[200:203], v207 offset:22528
	ds_read_b128 v[208:211], v207 offset:23552
	global_load_lds_dwordx4 v[194:195], off
	s_add_i32 m0, s4, 0x2000
	s_add_u32 s4, s78, 0x100000
	v_lshl_add_u64 v[212:213], s[78:79], 0, v[176:177]
	s_addc_u32 s5, s79, 0
	s_add_i32 s6, s7, s91
	global_load_lds_dwordx4 v[212:213], off
	v_lshl_add_u64 v[214:215], s[4:5], 0, v[172:173]
	s_mov_b32 m0, s6
	v_lshl_add_u64 v[216:217], vcc, 0, v[174:175]
	global_load_lds_dwordx4 v[214:215], off
	v_lshl_add_u64 v[214:215], s[4:5], 0, v[176:177]
	s_add_i32 m0, s6, 0x2000
	s_nop 0
	global_load_lds_dwordx4 v[214:215], off
	v_lshl_add_u64 v[214:215], vcc, 0, v[98:99]
	s_mov_b32 m0, s44
	s_nop 0
	global_load_lds_dwordx4 v[214:215], off
	s_add_i32 m0, s44, 0x2000
	s_nop 0
	global_load_lds_dwordx4 v[216:217], off
	s_waitcnt vmcnt(8)
	s_waitcnt lgkmcnt(0)
	s_setprio 1
	s_barrier
	v_mfma_f32_16x16x32_bf16 v[62:65], v[112:115], v[164:167], v[62:65]
	v_mfma_f32_16x16x32_bf16 v[58:61], v[124:127], v[164:167], v[58:61]
	v_mfma_f32_16x16x32_bf16 v[46:49], v[112:115], v[178:181], v[46:49]
	v_mfma_f32_16x16x32_bf16 v[42:45], v[124:127], v[178:181], v[42:45]
	v_mfma_f32_16x16x32_bf16 v[30:33], v[112:115], v[186:189], v[30:33]
	v_mfma_f32_16x16x32_bf16 v[26:29], v[124:127], v[186:189], v[26:29]
	v_mfma_f32_16x16x32_bf16 v[14:17], v[112:115], v[200:203], v[14:17]
	v_mfma_f32_16x16x32_bf16 v[10:13], v[124:127], v[200:203], v[10:13]
	v_mfma_f32_16x16x32_bf16 v[62:65], v[116:119], v[168:171], v[62:65]
	v_mfma_f32_16x16x32_bf16 v[58:61], v[128:131], v[168:171], v[58:61]
	v_mfma_f32_16x16x32_bf16 v[46:49], v[116:119], v[182:185], v[46:49]
	v_mfma_f32_16x16x32_bf16 v[42:45], v[128:131], v[182:185], v[42:45]
	v_mfma_f32_16x16x32_bf16 v[30:33], v[116:119], v[190:193], v[30:33]
	v_mfma_f32_16x16x32_bf16 v[26:29], v[128:131], v[190:193], v[26:29]
	v_mfma_f32_16x16x32_bf16 v[14:17], v[116:119], v[208:211], v[14:17]
	v_mfma_f32_16x16x32_bf16 v[10:13], v[128:131], v[208:211], v[10:13]
	s_setprio 0
	s_setprio 1
	v_mfma_f32_16x16x32_bf16 v[54:57], v[148:151], v[164:167], v[54:57]
	v_mfma_f32_16x16x32_bf16 v[50:53], v[156:159], v[164:167], v[50:53]
	v_mfma_f32_16x16x32_bf16 v[38:41], v[148:151], v[178:181], v[38:41]
	v_mfma_f32_16x16x32_bf16 v[34:37], v[156:159], v[178:181], v[34:37]
	v_mfma_f32_16x16x32_bf16 v[22:25], v[148:151], v[186:189], v[22:25]
	v_mfma_f32_16x16x32_bf16 v[18:21], v[156:159], v[186:189], v[18:21]
	v_mfma_f32_16x16x32_bf16 v[6:9], v[148:151], v[200:203], v[6:9]
	v_mfma_f32_16x16x32_bf16 v[2:5], v[156:159], v[200:203], v[2:5]
	v_mfma_f32_16x16x32_bf16 v[54:57], v[152:155], v[168:171], v[54:57]
	v_mfma_f32_16x16x32_bf16 v[50:53], v[160:163], v[168:171], v[50:53]
	v_mfma_f32_16x16x32_bf16 v[38:41], v[152:155], v[182:185], v[38:41]
	v_mfma_f32_16x16x32_bf16 v[34:37], v[160:163], v[182:185], v[34:37]
	v_mfma_f32_16x16x32_bf16 v[22:25], v[152:155], v[190:193], v[22:25]
	v_mfma_f32_16x16x32_bf16 v[18:21], v[160:163], v[190:193], v[18:21]
	v_mfma_f32_16x16x32_bf16 v[6:9], v[152:155], v[208:211], v[6:9]
	v_mfma_f32_16x16x32_bf16 v[2:5], v[160:163], v[208:211], v[2:5]
	s_setprio 0
	s_barrier
	s_add_i32 s6, 0, 0x18000
	s_add_i32 s7, 0, 0x1c000
	v_add_u32_e32 v128, s6, v205
	v_add_u32_e32 v160, s7, v205
	ds_read_b128 v[112:115], v128
	ds_read_b128 v[116:119], v128 offset:1024
	ds_read_b128 v[124:127], v128 offset:2048
	ds_read_b128 v[128:131], v128 offset:3072
	ds_read_b128 v[148:151], v160
	ds_read_b128 v[152:155], v160 offset:1024
	ds_read_b128 v[156:159], v160 offset:2048
	ds_read_b128 v[160:163], v160 offset:3072
	s_add_u32 s4, vcc_lo, 0x100000
	s_addc_u32 s5, vcc_hi, 0
	v_lshl_add_u64 v[218:219], s[4:5], 0, v[98:99]
	s_add_i32 m0, s44, 0x4000
	ds_read_b128 v[164:167], v207 offset:32768
	ds_read_b128 v[168:171], v207 offset:33792
	ds_read_b128 v[178:181], v207 offset:34816
	ds_read_b128 v[182:185], v207 offset:35840
	ds_read_b128 v[186:189], v207 offset:36864
	ds_read_b128 v[190:193], v207 offset:37888
	ds_read_b128 v[200:203], v207 offset:38912
	ds_read_b128 v[208:211], v207 offset:39936
	global_load_lds_dwordx4 v[218:219], off
	v_lshl_add_u64 v[218:219], s[4:5], 0, v[174:175]
	s_add_i32 m0, s44, 0x6000
	s_nop 0
	global_load_lds_dwordx4 v[218:219], off
	s_waitcnt vmcnt(8)
	s_waitcnt lgkmcnt(0)
	s_setprio 1
	s_barrier
	v_mfma_f32_16x16x32_bf16 v[144:147], v[112:115], v[164:167], v[144:147]
	v_mfma_f32_16x16x32_bf16 v[140:143], v[124:127], v[164:167], v[140:143]
	v_mfma_f32_16x16x32_bf16 v[120:123], v[112:115], v[178:181], v[120:123]
	v_mfma_f32_16x16x32_bf16 v[108:111], v[124:127], v[178:181], v[108:111]
	v_mfma_f32_16x16x32_bf16 v[94:97], v[112:115], v[186:189], v[94:97]
	v_mfma_f32_16x16x32_bf16 v[90:93], v[124:127], v[186:189], v[90:93]
	v_mfma_f32_16x16x32_bf16 v[78:81], v[112:115], v[200:203], v[78:81]
	v_mfma_f32_16x16x32_bf16 v[74:77], v[124:127], v[200:203], v[74:77]
	v_mfma_f32_16x16x32_bf16 v[144:147], v[116:119], v[168:171], v[144:147]
	v_mfma_f32_16x16x32_bf16 v[140:143], v[128:131], v[168:171], v[140:143]
	v_mfma_f32_16x16x32_bf16 v[120:123], v[116:119], v[182:185], v[120:123]
	v_mfma_f32_16x16x32_bf16 v[108:111], v[128:131], v[182:185], v[108:111]
	v_mfma_f32_16x16x32_bf16 v[94:97], v[116:119], v[190:193], v[94:97]
	v_mfma_f32_16x16x32_bf16 v[90:93], v[128:131], v[190:193], v[90:93]
	v_mfma_f32_16x16x32_bf16 v[78:81], v[116:119], v[208:211], v[78:81]
	v_mfma_f32_16x16x32_bf16 v[74:77], v[128:131], v[208:211], v[74:77]
	s_setprio 0
	s_setprio 1
	v_mfma_f32_16x16x32_bf16 v[136:139], v[148:151], v[164:167], v[136:139]
	v_mfma_f32_16x16x32_bf16 v[132:135], v[156:159], v[164:167], v[132:135]
	v_mfma_f32_16x16x32_bf16 v[104:107], v[148:151], v[178:181], v[104:107]
	v_mfma_f32_16x16x32_bf16 v[100:103], v[156:159], v[178:181], v[100:103]
	v_mfma_f32_16x16x32_bf16 v[86:89], v[148:151], v[186:189], v[86:89]
	v_mfma_f32_16x16x32_bf16 v[82:85], v[156:159], v[186:189], v[82:85]
	v_mfma_f32_16x16x32_bf16 v[70:73], v[148:151], v[200:203], v[70:73]
	v_mfma_f32_16x16x32_bf16 v[66:69], v[156:159], v[200:203], v[66:69]
	v_mfma_f32_16x16x32_bf16 v[136:139], v[152:155], v[168:171], v[136:139]
	v_mfma_f32_16x16x32_bf16 v[132:135], v[160:163], v[168:171], v[132:135]
	v_mfma_f32_16x16x32_bf16 v[104:107], v[152:155], v[182:185], v[104:107]
	v_mfma_f32_16x16x32_bf16 v[100:103], v[160:163], v[182:185], v[100:103]
	v_mfma_f32_16x16x32_bf16 v[86:89], v[152:155], v[190:193], v[86:89]
	v_mfma_f32_16x16x32_bf16 v[82:85], v[160:163], v[190:193], v[82:85]
	v_mfma_f32_16x16x32_bf16 v[70:73], v[152:155], v[208:211], v[70:73]
	v_mfma_f32_16x16x32_bf16 v[66:69], v[160:163], v[208:211], v[66:69]
	s_setprio 0
	s_barrier
	s_add_i32 s4, s6, s91
	v_lshl_add_u64 v[194:195], v[194:195], 0, s[42:43]
	s_mov_b32 m0, s4
	ds_read_b128 v[164:167], v207 offset:49152
	ds_read_b128 v[168:171], v207 offset:50176
	ds_read_b128 v[178:181], v207 offset:51200
	ds_read_b128 v[182:185], v207 offset:52224
	ds_read_b128 v[186:189], v207 offset:53248
	ds_read_b128 v[190:193], v207 offset:54272
	ds_read_b128 v[200:203], v207 offset:55296
	ds_read_b128 v[208:211], v207 offset:56320
	global_load_lds_dwordx4 v[194:195], off
	s_add_i32 m0, s4, 0x2000
	s_add_u32 s4, s78, 0x100080
	v_lshl_add_u64 v[194:195], v[212:213], 0, s[42:43]
	s_addc_u32 s5, s79, 0
	s_add_i32 s6, s7, s91
	global_load_lds_dwordx4 v[194:195], off
	v_lshl_add_u64 v[194:195], s[4:5], 0, v[172:173]
	s_mov_b32 m0, s6
	s_nop 0
	global_load_lds_dwordx4 v[194:195], off
	v_lshl_add_u64 v[194:195], s[4:5], 0, v[176:177]
	s_add_i32 m0, s6, 0x2000
	s_nop 0
	global_load_lds_dwordx4 v[194:195], off
	v_lshl_add_u64 v[194:195], v[214:215], 0, s[42:43]
	s_add_i32 m0, s44, 0x8000
	s_nop 0
	global_load_lds_dwordx4 v[194:195], off
	v_lshl_add_u64 v[194:195], v[216:217], 0, s[42:43]
	s_add_i32 m0, s44, 0xa000
	s_nop 0
	global_load_lds_dwordx4 v[194:195], off
	s_waitcnt vmcnt(8)
	s_waitcnt lgkmcnt(0)
	s_setprio 1
	s_barrier
	v_mfma_f32_16x16x32_bf16 v[62:65], v[112:115], v[164:167], v[62:65]
	v_mfma_f32_16x16x32_bf16 v[58:61], v[124:127], v[164:167], v[58:61]
	v_mfma_f32_16x16x32_bf16 v[46:49], v[112:115], v[178:181], v[46:49]
	v_mfma_f32_16x16x32_bf16 v[42:45], v[124:127], v[178:181], v[42:45]
	v_mfma_f32_16x16x32_bf16 v[30:33], v[112:115], v[186:189], v[30:33]
	v_mfma_f32_16x16x32_bf16 v[26:29], v[124:127], v[186:189], v[26:29]
	v_mfma_f32_16x16x32_bf16 v[14:17], v[112:115], v[200:203], v[14:17]
	v_mfma_f32_16x16x32_bf16 v[10:13], v[124:127], v[200:203], v[10:13]
	v_mfma_f32_16x16x32_bf16 v[62:65], v[116:119], v[168:171], v[62:65]
	v_mfma_f32_16x16x32_bf16 v[58:61], v[128:131], v[168:171], v[58:61]
	v_mfma_f32_16x16x32_bf16 v[46:49], v[116:119], v[182:185], v[46:49]
	v_mfma_f32_16x16x32_bf16 v[42:45], v[128:131], v[182:185], v[42:45]
	v_mfma_f32_16x16x32_bf16 v[30:33], v[116:119], v[190:193], v[30:33]
	v_mfma_f32_16x16x32_bf16 v[26:29], v[128:131], v[190:193], v[26:29]
	v_mfma_f32_16x16x32_bf16 v[14:17], v[116:119], v[208:211], v[14:17]
	v_mfma_f32_16x16x32_bf16 v[10:13], v[128:131], v[208:211], v[10:13]
	s_setprio 0
	s_setprio 1
	v_mfma_f32_16x16x32_bf16 v[54:57], v[148:151], v[164:167], v[54:57]
	v_mfma_f32_16x16x32_bf16 v[50:53], v[156:159], v[164:167], v[50:53]
	v_mfma_f32_16x16x32_bf16 v[38:41], v[148:151], v[178:181], v[38:41]
	v_mfma_f32_16x16x32_bf16 v[34:37], v[156:159], v[178:181], v[34:37]
	v_mfma_f32_16x16x32_bf16 v[22:25], v[148:151], v[186:189], v[22:25]
	v_mfma_f32_16x16x32_bf16 v[18:21], v[156:159], v[186:189], v[18:21]
	v_mfma_f32_16x16x32_bf16 v[6:9], v[148:151], v[200:203], v[6:9]
	v_mfma_f32_16x16x32_bf16 v[2:5], v[156:159], v[200:203], v[2:5]
	v_mfma_f32_16x16x32_bf16 v[54:57], v[152:155], v[168:171], v[54:57]
	v_mfma_f32_16x16x32_bf16 v[50:53], v[160:163], v[168:171], v[50:53]
	v_mfma_f32_16x16x32_bf16 v[38:41], v[152:155], v[182:185], v[38:41]
	v_mfma_f32_16x16x32_bf16 v[34:37], v[160:163], v[182:185], v[34:37]
	v_mfma_f32_16x16x32_bf16 v[22:25], v[152:155], v[190:193], v[22:25]
	v_mfma_f32_16x16x32_bf16 v[18:21], v[160:163], v[190:193], v[18:21]
	v_mfma_f32_16x16x32_bf16 v[6:9], v[152:155], v[208:211], v[6:9]
	v_mfma_f32_16x16x32_bf16 v[2:5], v[160:163], v[208:211], v[2:5]
	s_setprio 0
	s_barrier
	s_add_i32 s95, s95, 2
	s_add_u32 s74, s74, 0x100
	s_addc_u32 s75, s75, 0
	s_add_u32 s71, s71, 0x100
	s_addc_u32 s94, s94, 0
	s_cmp_gt_u32 s95, 61
	s_cbranch_scc0 .LBB0_1116
	s_mov_b32 s100, 1
	s_and_b64 vcc, exec, s[10:11]
	s_cbranch_vccz .LBB0_1119
	s_lshl_b32 s4, s70, 8
	v_add_u32_e32 v194, s4, v204
	s_addk_i32 s4, 0xc000
	s_lshr_b32 s4, s4, 12
	s_ashr_i32 s5, s70, 5
	s_add_i32 s4, s4, 2
	s_cmp_lt_i32 s70, 64
	v_lshl_or_b32 v178, s20, 8, v206
	s_cselect_b32 s4, s5, s4
	v_ashrrev_i32_e32 v179, 31, v178
	s_ashr_i32 s5, s4, 31
	v_lshlrev_b64 v[180:181], 1, v[178:179]
	v_ashrrev_i32_e32 v195, 31, v194
	s_lshl_b64 s[4:5], s[4:5], 14
	v_lshl_add_u64 v[148:149], s[82:83], 0, v[180:181]
	v_lshlrev_b64 v[214:215], 11, v[194:195]
	s_add_u32 s4, s89, s4
	v_lshl_add_u64 v[112:113], v[148:149], 0, v[214:215]
	s_addc_u32 s5, s90, s5
	global_load_dwordx4 v[200:203], v[112:113], off
	global_load_dwordx4 v[210:213], v[112:113], off offset:256
	v_lshl_add_u64 v[112:113], v[178:179], 2, s[4:5]
	global_load_dwordx4 v[128:131], v[112:113], off
	global_load_dwordx4 v[124:127], v[112:113], off offset:16
	global_load_dwordx4 v[116:119], v[112:113], off offset:512
	s_nop 0
	global_load_dwordx4 v[112:115], v[112:113], off offset:528
	v_or_b32_e32 v190, 16, v194
	v_or_b32_e32 v186, 32, v194
	v_or_b32_e32 v182, 48, v194
	v_ashrrev_i32_e32 v191, 31, v190
	v_ashrrev_i32_e32 v187, 31, v186
	v_ashrrev_i32_e32 v183, 31, v182
	v_lshlrev_b64 v[192:193], 11, v[190:191]
	v_lshlrev_b64 v[188:189], 11, v[186:187]
	v_lshlrev_b64 v[184:185], 11, v[182:183]
	v_lshl_add_u64 v[150:151], v[148:149], 0, v[192:193]
	v_lshl_add_u64 v[152:153], v[148:149], 0, v[188:189]
	v_lshl_add_u64 v[148:149], v[148:149], 0, v[184:185]
	global_load_dwordx4 v[168:171], v[150:151], off
	global_load_dwordx4 v[164:167], v[150:151], off offset:256
	global_load_dwordx4 v[160:163], v[152:153], off
	global_load_dwordx4 v[156:159], v[152:153], off offset:256
	s_nop 0
	global_load_dwordx4 v[152:155], v[148:149], off
	s_nop 0
	global_load_dwordx4 v[148:151], v[148:149], off offset:256
	s_barrier
	s_branch .Lmy_g4a_afterload

.Lmy_g4a_afterload:
	v_and_b32_e32 v209, 64, v229
	v_xor_b32_e32 v208, 16, v229
	v_add_u32_e32 v209, 64, v209
	v_xor_b32_e32 v216, 32, v229
	v_cmp_lt_i32_e32 vcc, v208, v209
	s_lshl_b32 s20, s20, 2
	s_ashr_i32 s21, s20, 31
	v_cndmask_b32_e32 v208, v229, v208, vcc
	v_cmp_lt_i32_e32 vcc, v216, v209
	v_lshlrev_b32_e32 v209, 2, v208
	s_waitcnt vmcnt(0)
	v_and_b32_e32 v217, 0xffff0000, v200
	v_cndmask_b32_e32 v216, v229, v216, vcc
	s_andn2_b64 vcc, exec, s[30:31]
	v_lshlrev_b32_e32 v208, 2, v216
	v_lshlrev_b32_e32 v216, 16, v200
	v_lshlrev_b32_e32 v200, 16, v201
	v_and_b32_e32 v201, 0xffff0000, v201
	v_lshlrev_b32_e32 v218, 16, v202
	v_and_b32_e32 v219, 0xffff0000, v202
	v_lshlrev_b32_e32 v202, 16, v203
	v_and_b32_e32 v203, 0xffff0000, v203
	v_lshlrev_b32_e32 v222, 16, v212
	v_and_b32_e32 v223, 0xffff0000, v212
	v_lshlrev_b32_e32 v212, 16, v213
	v_and_b32_e32 v213, 0xffff0000, v213
	v_lshlrev_b32_e32 v220, 16, v210
	v_and_b32_e32 v221, 0xffff0000, v210
	v_lshlrev_b32_e32 v210, 16, v211
	v_and_b32_e32 v211, 0xffff0000, v211
	v_pk_fma_f32 v[146:147], v[146:147], v[130:131], v[200:201]
	v_pk_fma_f32 v[142:143], v[142:143], v[126:127], v[202:203]
	v_pk_fma_f32 v[140:141], v[140:141], v[124:125], v[218:219]
	v_pk_fma_f32 v[200:201], v[134:135], v[114:115], v[212:213]
	v_pk_fma_f32 v[202:203], v[132:133], v[112:113], v[222:223]
	v_pk_fma_f32 v[144:145], v[144:145], v[128:129], v[216:217]
	v_pk_fma_f32 v[136:137], v[136:137], v[116:117], v[220:221]
	v_pk_fma_f32 v[138:139], v[138:139], v[118:119], v[210:211]
	v_pk_mul_f32 v[210:211], v[140:141], v[140:141]
	v_pk_mul_f32 v[212:213], v[142:143], v[142:143]
	v_cvt_pk_bf16_f32 v134, v140, v141
	v_cvt_pk_bf16_f32 v135, v142, v143
	v_pk_mul_f32 v[140:141], v[202:203], v[202:203]
	v_pk_mul_f32 v[142:143], v[200:201], v[200:201]
	v_cvt_pk_bf16_f32 v132, v144, v145
	v_cvt_pk_bf16_f32 v133, v146, v147
	v_pk_fma_f32 v[146:147], v[146:147], v[146:147], v[212:213]
	v_pk_fma_f32 v[144:145], v[144:145], v[144:145], v[210:211]
	v_pk_fma_f32 v[142:143], v[138:139], v[138:139], v[142:143]
	v_pk_fma_f32 v[140:141], v[136:137], v[136:137], v[140:141]
	v_add_f32_e32 v144, v144, v145
	v_add_f32_e32 v145, v146, v147
	v_add_f32_e32 v140, v140, v141
	v_add_f32_e32 v142, v142, v143
	v_add_f32_e32 v141, v144, v145
	v_add_f32_e32 v140, v140, v142
	v_add_f32_e32 v142, v141, v140
	ds_bpermute_b32 v143, v209, v142
	v_lshl_add_u64 v[140:141], s[22:23], 0, v[214:215]
	v_lshl_add_u64 v[140:141], v[140:141], 0, v[180:181]
	s_cbranch_vccnz .Lmy_wt_g4a_0
	global_store_dwordx4 v[140:141], v[132:135], off

.LBB0_1172:
	s_add_u32 s4, s70, 0xfff00080
	s_addc_u32 s5, s71, -1
	s_add_i32 s6, 0, 0x10000
	s_cmp_eq_u32 s95, 60
	s_cselect_b32 s79, s18, s5
	s_cselect_b32 s78, s27, s4
	s_cselect_b32 s75, s15, s94
	s_cselect_b32 s74, s57, s69
	s_add_i32 s7, 0, 0x14000
	v_add_u32_e32 v104, s6, v239
	v_add_u32_e32 v128, s7, v239
	ds_read_b128 v[90:93], v104
	ds_read_b128 v[94:97], v104 offset:1024
	ds_read_b128 v[100:103], v104 offset:2048
	ds_read_b128 v[104:107], v104 offset:3072
	ds_read_b128 v[108:111], v128
	ds_read_b128 v[112:115], v128 offset:1024
	ds_read_b128 v[120:123], v128 offset:2048
	ds_read_b128 v[128:131], v128 offset:3072
	s_add_i32 s44, s91, 0
	v_lshl_add_u64 v[200:201], s[70:71], 0, v[98:99]
	s_add_i32 m0, s44, 0xc000
	ds_read_b128 v[164:167], v241
	ds_read_b128 v[168:171], v241 offset:1024
	ds_read_b128 v[172:175], v241 offset:2048
	ds_read_b128 v[176:179], v241 offset:3072
	ds_read_b128 v[180:183], v241 offset:4096
	ds_read_b128 v[184:187], v241 offset:5120
	ds_read_b128 v[188:191], v241 offset:6144
	ds_read_b128 v[192:195], v241 offset:7168
	global_load_lds_dwordx4 v[200:201], off
	v_lshl_add_u64 v[200:201], s[70:71], 0, v[206:207]
	s_add_i32 m0, s44, 0xe000
	s_nop 0
	global_load_lds_dwordx4 v[200:201], off
	s_waitcnt vmcnt(8)
	s_waitcnt lgkmcnt(0)
	s_setprio 1
	s_barrier
	v_mfma_f32_16x16x32_bf16 v[160:163], v[90:93], v[164:167], v[160:163]
	v_mfma_f32_16x16x32_bf16 v[156:159], v[100:103], v[164:167], v[156:159]
	v_mfma_f32_16x16x32_bf16 v[144:147], v[90:93], v[172:175], v[144:147]
	v_mfma_f32_16x16x32_bf16 v[140:143], v[100:103], v[172:175], v[140:143]
	v_mfma_f32_16x16x32_bf16 v[124:127], v[90:93], v[180:183], v[124:127]
	v_mfma_f32_16x16x32_bf16 v[116:119], v[100:103], v[180:183], v[116:119]
	v_mfma_f32_16x16x32_bf16 v[78:81], v[90:93], v[188:191], v[78:81]
	v_mfma_f32_16x16x32_bf16 v[74:77], v[100:103], v[188:191], v[74:77]
	v_mfma_f32_16x16x32_bf16 v[160:163], v[94:97], v[168:171], v[160:163]
	v_mfma_f32_16x16x32_bf16 v[156:159], v[104:107], v[168:171], v[156:159]
	v_mfma_f32_16x16x32_bf16 v[144:147], v[94:97], v[176:179], v[144:147]
	v_mfma_f32_16x16x32_bf16 v[140:143], v[104:107], v[176:179], v[140:143]
	v_mfma_f32_16x16x32_bf16 v[124:127], v[94:97], v[184:187], v[124:127]
	v_mfma_f32_16x16x32_bf16 v[116:119], v[104:107], v[184:187], v[116:119]
	v_mfma_f32_16x16x32_bf16 v[78:81], v[94:97], v[192:195], v[78:81]
	v_mfma_f32_16x16x32_bf16 v[74:77], v[104:107], v[192:195], v[74:77]
	s_setprio 0
	s_setprio 1
	v_mfma_f32_16x16x32_bf16 v[152:155], v[108:111], v[164:167], v[152:155]
	v_mfma_f32_16x16x32_bf16 v[148:151], v[120:123], v[164:167], v[148:151]
	v_mfma_f32_16x16x32_bf16 v[136:139], v[108:111], v[172:175], v[136:139]
	v_mfma_f32_16x16x32_bf16 v[132:135], v[120:123], v[172:175], v[132:135]
	v_mfma_f32_16x16x32_bf16 v[86:89], v[108:111], v[180:183], v[86:89]
	v_mfma_f32_16x16x32_bf16 v[82:85], v[120:123], v[180:183], v[82:85]
	v_mfma_f32_16x16x32_bf16 v[70:73], v[108:111], v[188:191], v[70:73]
	v_mfma_f32_16x16x32_bf16 v[66:69], v[120:123], v[188:191], v[66:69]
	v_mfma_f32_16x16x32_bf16 v[152:155], v[112:115], v[168:171], v[152:155]
	v_mfma_f32_16x16x32_bf16 v[148:151], v[128:131], v[168:171], v[148:151]
	v_mfma_f32_16x16x32_bf16 v[136:139], v[112:115], v[176:179], v[136:139]
	v_mfma_f32_16x16x32_bf16 v[132:135], v[128:131], v[176:179], v[132:135]
	v_mfma_f32_16x16x32_bf16 v[86:89], v[112:115], v[184:187], v[86:89]
	v_mfma_f32_16x16x32_bf16 v[82:85], v[128:131], v[184:187], v[82:85]
	v_mfma_f32_16x16x32_bf16 v[70:73], v[112:115], v[192:195], v[70:73]
	v_mfma_f32_16x16x32_bf16 v[66:69], v[128:131], v[192:195], v[66:69]
	s_setprio 0
	s_barrier
	s_add_i32 s4, s6, s91
	v_lshl_add_u64 v[200:201], s[74:75], 0, v[204:205]
	s_mov_b32 m0, s4
	ds_read_b128 v[164:167], v241 offset:16384
	ds_read_b128 v[168:171], v241 offset:17408
	ds_read_b128 v[172:175], v241 offset:18432
	ds_read_b128 v[176:179], v241 offset:19456
	ds_read_b128 v[180:183], v241 offset:20480
	ds_read_b128 v[184:187], v241 offset:21504
	ds_read_b128 v[188:191], v241 offset:22528
	ds_read_b128 v[192:195], v241 offset:23552
	global_load_lds_dwordx4 v[200:201], off
	s_add_i32 m0, s4, 0x2000
	s_add_u32 s4, s74, 0x100000
	v_lshl_add_u64 v[202:203], s[74:75], 0, v[208:209]
	s_addc_u32 s5, s75, 0
	s_add_i32 s6, s7, s91
	global_load_lds_dwordx4 v[202:203], off
	v_lshl_add_u64 v[210:211], s[4:5], 0, v[204:205]
	s_mov_b32 m0, s6
	v_lshl_add_u64 v[212:213], s[78:79], 0, v[206:207]
	global_load_lds_dwordx4 v[210:211], off
	v_lshl_add_u64 v[210:211], s[4:5], 0, v[208:209]
	s_add_i32 m0, s6, 0x2000
	s_nop 0
	global_load_lds_dwordx4 v[210:211], off
	v_lshl_add_u64 v[210:211], s[78:79], 0, v[98:99]
	s_mov_b32 m0, s44
	s_nop 0
	global_load_lds_dwordx4 v[210:211], off
	s_add_i32 m0, s44, 0x2000
	s_nop 0
	global_load_lds_dwordx4 v[212:213], off
	s_waitcnt vmcnt(8)
	s_waitcnt lgkmcnt(0)
	s_setprio 1
	s_barrier
	v_mfma_f32_16x16x32_bf16 v[62:65], v[90:93], v[164:167], v[62:65]
	v_mfma_f32_16x16x32_bf16 v[58:61], v[100:103], v[164:167], v[58:61]
	v_mfma_f32_16x16x32_bf16 v[46:49], v[90:93], v[172:175], v[46:49]
	v_mfma_f32_16x16x32_bf16 v[42:45], v[100:103], v[172:175], v[42:45]
	v_mfma_f32_16x16x32_bf16 v[30:33], v[90:93], v[180:183], v[30:33]
	v_mfma_f32_16x16x32_bf16 v[26:29], v[100:103], v[180:183], v[26:29]
	v_mfma_f32_16x16x32_bf16 v[14:17], v[90:93], v[188:191], v[14:17]
	v_mfma_f32_16x16x32_bf16 v[10:13], v[100:103], v[188:191], v[10:13]
	v_mfma_f32_16x16x32_bf16 v[62:65], v[94:97], v[168:171], v[62:65]
	v_mfma_f32_16x16x32_bf16 v[58:61], v[104:107], v[168:171], v[58:61]
	v_mfma_f32_16x16x32_bf16 v[46:49], v[94:97], v[176:179], v[46:49]
	v_mfma_f32_16x16x32_bf16 v[42:45], v[104:107], v[176:179], v[42:45]
	v_mfma_f32_16x16x32_bf16 v[30:33], v[94:97], v[184:187], v[30:33]
	v_mfma_f32_16x16x32_bf16 v[26:29], v[104:107], v[184:187], v[26:29]
	v_mfma_f32_16x16x32_bf16 v[14:17], v[94:97], v[192:195], v[14:17]
	v_mfma_f32_16x16x32_bf16 v[10:13], v[104:107], v[192:195], v[10:13]
	s_setprio 0
	s_setprio 1
	v_mfma_f32_16x16x32_bf16 v[54:57], v[108:111], v[164:167], v[54:57]
	v_mfma_f32_16x16x32_bf16 v[50:53], v[120:123], v[164:167], v[50:53]
	v_mfma_f32_16x16x32_bf16 v[38:41], v[108:111], v[172:175], v[38:41]
	v_mfma_f32_16x16x32_bf16 v[34:37], v[120:123], v[172:175], v[34:37]
	v_mfma_f32_16x16x32_bf16 v[22:25], v[108:111], v[180:183], v[22:25]
	v_mfma_f32_16x16x32_bf16 v[18:21], v[120:123], v[180:183], v[18:21]
	v_mfma_f32_16x16x32_bf16 v[6:9], v[108:111], v[188:191], v[6:9]
	v_mfma_f32_16x16x32_bf16 v[2:5], v[120:123], v[188:191], v[2:5]
	v_mfma_f32_16x16x32_bf16 v[54:57], v[112:115], v[168:171], v[54:57]
	v_mfma_f32_16x16x32_bf16 v[50:53], v[128:131], v[168:171], v[50:53]
	v_mfma_f32_16x16x32_bf16 v[38:41], v[112:115], v[176:179], v[38:41]
	v_mfma_f32_16x16x32_bf16 v[34:37], v[128:131], v[176:179], v[34:37]
	v_mfma_f32_16x16x32_bf16 v[22:25], v[112:115], v[184:187], v[22:25]
	v_mfma_f32_16x16x32_bf16 v[18:21], v[128:131], v[184:187], v[18:21]
	v_mfma_f32_16x16x32_bf16 v[6:9], v[112:115], v[192:195], v[6:9]
	v_mfma_f32_16x16x32_bf16 v[2:5], v[128:131], v[192:195], v[2:5]
	s_setprio 0
	s_barrier
	s_add_i32 s6, 0, 0x18000
	s_add_i32 s7, 0, 0x1c000
	v_add_u32_e32 v104, s6, v239
	v_add_u32_e32 v128, s7, v239
	ds_read_b128 v[90:93], v104
	ds_read_b128 v[94:97], v104 offset:1024
	ds_read_b128 v[100:103], v104 offset:2048
	ds_read_b128 v[104:107], v104 offset:3072
	ds_read_b128 v[108:111], v128
	ds_read_b128 v[112:115], v128 offset:1024
	ds_read_b128 v[120:123], v128 offset:2048
	ds_read_b128 v[128:131], v128 offset:3072
	s_add_u32 s4, s78, 0x100000
	s_addc_u32 s5, s79, 0
	v_lshl_add_u64 v[214:215], s[4:5], 0, v[98:99]
	s_add_i32 m0, s44, 0x4000
	ds_read_b128 v[164:167], v241 offset:32768
	ds_read_b128 v[168:171], v241 offset:33792
	ds_read_b128 v[172:175], v241 offset:34816
	ds_read_b128 v[176:179], v241 offset:35840
	ds_read_b128 v[180:183], v241 offset:36864
	ds_read_b128 v[184:187], v241 offset:37888
	ds_read_b128 v[188:191], v241 offset:38912
	ds_read_b128 v[192:195], v241 offset:39936
	global_load_lds_dwordx4 v[214:215], off
	v_lshl_add_u64 v[214:215], s[4:5], 0, v[206:207]
	s_add_i32 m0, s44, 0x6000
	s_nop 0
	global_load_lds_dwordx4 v[214:215], off
	s_waitcnt vmcnt(8)
	s_waitcnt lgkmcnt(0)
	s_setprio 1
	s_barrier
	v_mfma_f32_16x16x32_bf16 v[160:163], v[90:93], v[164:167], v[160:163]
	v_mfma_f32_16x16x32_bf16 v[156:159], v[100:103], v[164:167], v[156:159]
	v_mfma_f32_16x16x32_bf16 v[144:147], v[90:93], v[172:175], v[144:147]
	v_mfma_f32_16x16x32_bf16 v[140:143], v[100:103], v[172:175], v[140:143]
	v_mfma_f32_16x16x32_bf16 v[124:127], v[90:93], v[180:183], v[124:127]
	v_mfma_f32_16x16x32_bf16 v[116:119], v[100:103], v[180:183], v[116:119]
	v_mfma_f32_16x16x32_bf16 v[78:81], v[90:93], v[188:191], v[78:81]
	v_mfma_f32_16x16x32_bf16 v[74:77], v[100:103], v[188:191], v[74:77]
	v_mfma_f32_16x16x32_bf16 v[160:163], v[94:97], v[168:171], v[160:163]
	v_mfma_f32_16x16x32_bf16 v[156:159], v[104:107], v[168:171], v[156:159]
	v_mfma_f32_16x16x32_bf16 v[144:147], v[94:97], v[176:179], v[144:147]
	v_mfma_f32_16x16x32_bf16 v[140:143], v[104:107], v[176:179], v[140:143]
	v_mfma_f32_16x16x32_bf16 v[124:127], v[94:97], v[184:187], v[124:127]
	v_mfma_f32_16x16x32_bf16 v[116:119], v[104:107], v[184:187], v[116:119]
	v_mfma_f32_16x16x32_bf16 v[78:81], v[94:97], v[192:195], v[78:81]
	v_mfma_f32_16x16x32_bf16 v[74:77], v[104:107], v[192:195], v[74:77]
	s_setprio 0
	s_setprio 1
	v_mfma_f32_16x16x32_bf16 v[152:155], v[108:111], v[164:167], v[152:155]
	v_mfma_f32_16x16x32_bf16 v[148:151], v[120:123], v[164:167], v[148:151]
	v_mfma_f32_16x16x32_bf16 v[136:139], v[108:111], v[172:175], v[136:139]
	v_mfma_f32_16x16x32_bf16 v[132:135], v[120:123], v[172:175], v[132:135]
	v_mfma_f32_16x16x32_bf16 v[86:89], v[108:111], v[180:183], v[86:89]
	v_mfma_f32_16x16x32_bf16 v[82:85], v[120:123], v[180:183], v[82:85]
	v_mfma_f32_16x16x32_bf16 v[70:73], v[108:111], v[188:191], v[70:73]
	v_mfma_f32_16x16x32_bf16 v[66:69], v[120:123], v[188:191], v[66:69]
	v_mfma_f32_16x16x32_bf16 v[152:155], v[112:115], v[168:171], v[152:155]
	v_mfma_f32_16x16x32_bf16 v[148:151], v[128:131], v[168:171], v[148:151]
	v_mfma_f32_16x16x32_bf16 v[136:139], v[112:115], v[176:179], v[136:139]
	v_mfma_f32_16x16x32_bf16 v[132:135], v[128:131], v[176:179], v[132:135]
	v_mfma_f32_16x16x32_bf16 v[86:89], v[112:115], v[184:187], v[86:89]
	v_mfma_f32_16x16x32_bf16 v[82:85], v[128:131], v[184:187], v[82:85]
	v_mfma_f32_16x16x32_bf16 v[70:73], v[112:115], v[192:195], v[70:73]
	v_mfma_f32_16x16x32_bf16 v[66:69], v[128:131], v[192:195], v[66:69]
	s_setprio 0
	s_barrier
	s_add_i32 s4, s6, s91
	v_lshl_add_u64 v[200:201], v[200:201], 0, s[42:43]
	s_mov_b32 m0, s4
	ds_read_b128 v[164:167], v241 offset:49152
	ds_read_b128 v[168:171], v241 offset:50176
	ds_read_b128 v[172:175], v241 offset:51200
	ds_read_b128 v[176:179], v241 offset:52224
	ds_read_b128 v[180:183], v241 offset:53248
	ds_read_b128 v[184:187], v241 offset:54272
	ds_read_b128 v[188:191], v241 offset:55296
	ds_read_b128 v[192:195], v241 offset:56320
	global_load_lds_dwordx4 v[200:201], off
	s_add_i32 m0, s4, 0x2000
	s_add_u32 s4, s74, 0x100080
	v_lshl_add_u64 v[200:201], v[202:203], 0, s[42:43]
	s_addc_u32 s5, s75, 0
	s_add_i32 s6, s7, s91
	global_load_lds_dwordx4 v[200:201], off
	v_lshl_add_u64 v[200:201], s[4:5], 0, v[204:205]
	s_mov_b32 m0, s6
	s_nop 0
	global_load_lds_dwordx4 v[200:201], off
	v_lshl_add_u64 v[200:201], s[4:5], 0, v[208:209]
	s_add_i32 m0, s6, 0x2000
	s_nop 0
	global_load_lds_dwordx4 v[200:201], off
	v_lshl_add_u64 v[200:201], v[210:211], 0, s[42:43]
	s_add_i32 m0, s44, 0x8000
	s_nop 0
	global_load_lds_dwordx4 v[200:201], off
	v_lshl_add_u64 v[200:201], v[212:213], 0, s[42:43]
	s_add_i32 m0, s44, 0xa000
	s_nop 0
	global_load_lds_dwordx4 v[200:201], off
	s_waitcnt vmcnt(8)
	s_waitcnt lgkmcnt(0)
	s_setprio 1
	s_barrier
	v_mfma_f32_16x16x32_bf16 v[62:65], v[90:93], v[164:167], v[62:65]
	v_mfma_f32_16x16x32_bf16 v[58:61], v[100:103], v[164:167], v[58:61]
	v_mfma_f32_16x16x32_bf16 v[46:49], v[90:93], v[172:175], v[46:49]
	v_mfma_f32_16x16x32_bf16 v[42:45], v[100:103], v[172:175], v[42:45]
	v_mfma_f32_16x16x32_bf16 v[30:33], v[90:93], v[180:183], v[30:33]
	v_mfma_f32_16x16x32_bf16 v[26:29], v[100:103], v[180:183], v[26:29]
	v_mfma_f32_16x16x32_bf16 v[14:17], v[90:93], v[188:191], v[14:17]
	v_mfma_f32_16x16x32_bf16 v[10:13], v[100:103], v[188:191], v[10:13]
	v_mfma_f32_16x16x32_bf16 v[62:65], v[94:97], v[168:171], v[62:65]
	v_mfma_f32_16x16x32_bf16 v[58:61], v[104:107], v[168:171], v[58:61]
	v_mfma_f32_16x16x32_bf16 v[46:49], v[94:97], v[176:179], v[46:49]
	v_mfma_f32_16x16x32_bf16 v[42:45], v[104:107], v[176:179], v[42:45]
	v_mfma_f32_16x16x32_bf16 v[30:33], v[94:97], v[184:187], v[30:33]
	v_mfma_f32_16x16x32_bf16 v[26:29], v[104:107], v[184:187], v[26:29]
	v_mfma_f32_16x16x32_bf16 v[14:17], v[94:97], v[192:195], v[14:17]
	v_mfma_f32_16x16x32_bf16 v[10:13], v[104:107], v[192:195], v[10:13]
	s_setprio 0
	s_setprio 1
	v_mfma_f32_16x16x32_bf16 v[54:57], v[108:111], v[164:167], v[54:57]
	v_mfma_f32_16x16x32_bf16 v[50:53], v[120:123], v[164:167], v[50:53]
	v_mfma_f32_16x16x32_bf16 v[38:41], v[108:111], v[172:175], v[38:41]
	v_mfma_f32_16x16x32_bf16 v[34:37], v[120:123], v[172:175], v[34:37]
	v_mfma_f32_16x16x32_bf16 v[22:25], v[108:111], v[180:183], v[22:25]
	v_mfma_f32_16x16x32_bf16 v[18:21], v[120:123], v[180:183], v[18:21]
	v_mfma_f32_16x16x32_bf16 v[6:9], v[108:111], v[188:191], v[6:9]
	v_mfma_f32_16x16x32_bf16 v[2:5], v[120:123], v[188:191], v[2:5]
	v_mfma_f32_16x16x32_bf16 v[54:57], v[112:115], v[168:171], v[54:57]
	v_mfma_f32_16x16x32_bf16 v[50:53], v[128:131], v[168:171], v[50:53]
	v_mfma_f32_16x16x32_bf16 v[38:41], v[112:115], v[176:179], v[38:41]
	v_mfma_f32_16x16x32_bf16 v[34:37], v[128:131], v[176:179], v[34:37]
	v_mfma_f32_16x16x32_bf16 v[22:25], v[112:115], v[184:187], v[22:25]
	v_mfma_f32_16x16x32_bf16 v[18:21], v[128:131], v[184:187], v[18:21]
	v_mfma_f32_16x16x32_bf16 v[6:9], v[112:115], v[192:195], v[6:9]
	v_mfma_f32_16x16x32_bf16 v[2:5], v[128:131], v[192:195], v[2:5]
	s_setprio 0
	s_barrier
	s_add_i32 s95, s95, 2
	s_add_u32 s70, s70, 0x100
	s_addc_u32 s71, s71, 0
	s_add_u32 s69, s69, 0x100
	s_addc_u32 s94, s94, 0
	s_cmp_gt_u32 s95, 61
	s_cbranch_scc0 .LBB0_1172
	s_mov_b32 s100, 1
	s_and_b64 vcc, exec, s[10:11]
	s_cbranch_vccz .LBB0_1175
	s_lshl_b32 s6, s68, 8
	s_add_i32 s5, s6, 0xffffc000
	s_lshr_b32 s5, s5, 12
	s_ashr_i32 s4, s68, 5
	s_add_i32 s5, s5, 2
	s_cmp_lt_i32 s68, 64
	s_cselect_b32 s4, s4, s5
	s_ashr_i32 s5, s4, 31
	s_lshl_b64 s[4:5], s[4:5], 14
	v_lshl_or_b32 v164, s56, 8, v240
	s_add_u32 s44, s89, s4
	s_addc_u32 s45, s90, s5
	v_ashrrev_i32_e32 v165, 31, v164
	v_add_u32_e32 v222, s6, v238
	s_add_u32 s4, s8, s4
	v_lshlrev_b64 v[210:211], 1, v[164:165]
	v_ashrrev_i32_e32 v223, 31, v222
	v_lshlrev_b64 v[90:91], 2, v[164:165]
	s_addc_u32 s5, s9, s5
	v_lshl_add_u64 v[164:165], s[82:83], 0, v[210:211]
	v_lshlrev_b64 v[226:227], 11, v[222:223]
	v_lshl_add_u64 v[92:93], s[44:45], 0, v[90:91]
	v_lshl_add_u64 v[94:95], s[4:5], 0, v[90:91]
	v_lshl_add_u64 v[166:167], v[164:165], 0, v[226:227]
	global_load_dwordx4 v[120:123], v[92:93], off offset:16
	global_load_dwordx4 v[128:131], v[92:93], off
	global_load_dwordx4 v[108:111], v[94:95], off offset:16
	global_load_dwordx4 v[112:115], v[94:95], off
	global_load_dwordx4 v[100:103], v[92:93], off offset:528
	global_load_dwordx4 v[104:107], v[92:93], off offset:512
	s_nop 0
	global_load_dwordx4 v[90:93], v[94:95], off offset:528
	s_nop 0
	global_load_dwordx4 v[94:97], v[94:95], off offset:512
	s_nop 0
	global_load_dwordx4 v[192:195], v[166:167], off
	global_load_dwordx4 v[188:191], v[166:167], off offset:256
	v_or_b32_e32 v220, 16, v222
	v_ashrrev_i32_e32 v221, 31, v220
	v_or_b32_e32 v216, 32, v222
	v_or_b32_e32 v212, 48, v222
	v_lshlrev_b64 v[224:225], 11, v[220:221]
	v_ashrrev_i32_e32 v217, 31, v216
	v_ashrrev_i32_e32 v213, 31, v212
	v_lshl_add_u64 v[166:167], v[164:165], 0, v[224:225]
	v_lshlrev_b64 v[218:219], 11, v[216:217]
	v_lshlrev_b64 v[214:215], 11, v[212:213]
	global_load_dwordx4 v[184:187], v[166:167], off
	global_load_dwordx4 v[180:183], v[166:167], off offset:256
	v_lshl_add_u64 v[166:167], v[164:165], 0, v[218:219]
	v_lshl_add_u64 v[164:165], v[164:165], 0, v[214:215]
	global_load_dwordx4 v[176:179], v[166:167], off
	global_load_dwordx4 v[172:175], v[166:167], off offset:256
	global_load_dwordx4 v[168:171], v[164:165], off
	s_nop 0
	global_load_dwordx4 v[164:167], v[164:165], off offset:256
	s_barrier
	s_branch .Lmy_g4b_afterload

.Lmy_g4b_afterload:
	v_and_b32_e32 v201, 64, v229
	v_xor_b32_e32 v200, 16, v229
	v_add_u32_e32 v201, 64, v201
	v_cmp_lt_i32_e32 vcc, v200, v201
	s_lshl_b32 s56, s56, 2
	s_ashr_i32 s57, s56, 31
	v_cndmask_b32_e32 v200, v229, v200, vcc
	v_lshlrev_b32_e32 v242, 2, v200
	v_xor_b32_e32 v200, 32, v229
	v_cmp_lt_i32_e32 vcc, v200, v201
	s_waitcnt vmcnt(0)
	v_and_b32_e32 v201, 0xffff0000, v192
	v_cndmask_b32_e32 v200, v229, v200, vcc
	s_andn2_b64 vcc, exec, s[30:31]
	v_lshlrev_b32_e32 v243, 2, v200
	v_lshlrev_b32_e32 v200, 16, v192
	v_lshlrev_b32_e32 v192, 16, v193
	v_and_b32_e32 v193, 0xffff0000, v193
	v_lshlrev_b32_e32 v202, 16, v194
	v_and_b32_e32 v203, 0xffff0000, v194
	v_lshlrev_b32_e32 v194, 16, v195
	v_and_b32_e32 v195, 0xffff0000, v195
	v_pk_fma_f32 v[162:163], v[162:163], v[130:131], v[192:193]
	v_pk_fma_f32 v[192:193], v[158:159], v[122:123], v[194:195]
	v_pk_fma_f32 v[194:195], v[156:157], v[120:121], v[202:203]
	v_pk_fma_f32 v[160:161], v[160:161], v[128:129], v[200:201]
	v_pk_mul_f32 v[156:157], v[194:195], v[194:195]
	v_pk_mul_f32 v[158:159], v[192:193], v[192:193]
	v_pk_fma_f32 v[156:157], v[160:161], v[160:161], v[156:157]
	v_pk_fma_f32 v[158:159], v[162:163], v[162:163], v[158:159]
	v_add_f32_e32 v156, v156, v157
	v_add_f32_e32 v157, v158, v159
	v_lshl_add_u64 v[200:201], s[82:83], 0, v[226:227]
	v_add_f32_e32 v202, v156, v157
	v_cvt_pk_bf16_f32 v156, v160, v161
	v_cvt_pk_bf16_f32 v157, v162, v163
	v_cvt_pk_bf16_f32 v158, v194, v195
	v_cvt_pk_bf16_f32 v159, v192, v193
	v_lshl_add_u64 v[200:201], v[200:201], 0, v[210:211]
	s_cbranch_vccnz .Lmy_wt_g4b_0
	global_store_dwordx4 v[200:201], v[156:159], off
